# v50 + DPP/permlane16_swap wave_sum butterfly replacing ds_swizzle round trips (rowpass, combine, norm, final); bit-identical sums
# speedup vs baseline: 1.0022x; 1.0006x over previous
; __device__ __forceinline__ float wave_sum(float v) {
;     v += swz_xor<1>(v); v += swz_xor<2>(v); v += swz_xor<4>(v); v += swz_xor<8>(v); v += swz_xor<16>(v);
;     const auto rr = __builtin_amdgcn_permlane32_swap(__float_as_uint(v), __float_as_uint(v), false, false);
; __device__ __forceinline__ void mla_rowpass_phase(const Frame& F, int j, const bf16_t* CQKV, bf16_t* CN, bf16_t* KR, int rows, int grow0) {
;     ...
;     for (int r = F.gw; r < rows; r += F.NGW) {
;         const bf16_t* src = CQKV + (size_t)r * MA_N;
;         const u32x4 wq = *(const GAS u32x4*)(src + F.lane * 8), wk = *(const GAS u32x4*)(src + 512 + F.lane * 8);
;         float q[8], k[8]; float sq = 0.f, sk = 0.f;
; #pragma unroll
;         for (int e = 0; e < 4; ++e) { q[2 * e] = bf_lo(wq[e]); q[2 * e + 1] = bf_hi(wq[e]); k[2 * e] = bf_lo(wk[e]); k[2 * e + 1] = bf_hi(wk[e]);
;             sq += q[2 * e] * q[2 * e] + q[2 * e + 1] * q[2 * e + 1]; sk += k[2 * e] * k[2 * e] + k[2 * e + 1] * k[2 * e + 1]; }
;         const float rq = 1.0f / sqrtf(wave_sum(sq) * (1.f / 512.f) + NORM_EPS), rk = 1.0f / sqrtf(wave_sum(sk) * (1.f / 512.f) + NORM_EPS);
;         const f32x4 gq0 = *((const GAS f32x4*)gq + 2 * F.lane), gq1 = *((const GAS f32x4*)gq + 2 * F.lane + 1), gk0 = *((const GAS f32x4*)gkv + 2 * F.lane), gk1 = *((const GAS f32x4*)gkv + 2 * F.lane + 1);
;         u32x4 oq, ok;
;         oq.x = cvt_pk_bf16(q[0] * rq * gq0[0], q[1] * rq * gq0[1]); oq.y = cvt_pk_bf16(q[2] * rq * gq0[2], q[3] * rq * gq0[3]); oq.z = cvt_pk_bf16(q[4] * rq * gq1[0], q[5] * rq * gq1[1]); oq.w = cvt_pk_bf16(q[6] * rq * gq1[2], q[7] * rq * gq1[3]);
;         ok.x = cvt_pk_bf16(k[0] * rk * gk0[0], k[1] * rk * gk0[1]); ok.y = cvt_pk_bf16(k[2] * rk * gk0[2], k[3] * rk * gk0[3]); ok.z = cvt_pk_bf16(k[4] * rk * gk1[0], k[5] * rk * gk1[1]); ok.w = cvt_pk_bf16(k[6] * rk * gk1[2], k[7] * rk * gk1[3]);
;         *(GAS u32x4*)(CN + (size_t)r * 1024 + F.lane * 8) = oq; *(GAS u32x4*)(CN + (size_t)r * 1024 + 512 + F.lane * 8) = ok;
;         if (F.lane < 32) {
;             const unsigned w = *(const GAS unsigned*)(src + 1024 + 2 * F.lane); int t = row_tpos(grow0 + r); t = t < 0 ? 0 : t;
;             const float x1 = bf_lo(w), x2 = bf_hi(w), c = cosM[(size_t)t * 32 + F.lane], s = sinM[(size_t)t * 32 + F.lane];
;             *(GAS unsigned*)(KR + (size_t)r * 64 + 2 * F.lane) = cvt_pk_bf16(x1 * c - x2 * s, x1 * s + x2 * c);
;         }
.LBB0_356:
	v_lshl_add_u64 v[4:5], s[40:41], 0, v[24:25]
	global_load_dwordx4 v[0:3], v[4:5], off offset:-2048
	s_nop 0
	global_load_dwordx4 v[4:7], v[4:5], off offset:-1024
	s_waitcnt vmcnt(0)
	v_lshlrev_b32_e32 v32, 16, v0
	v_lshlrev_b32_e32 v36, 16, v1
	v_and_b32_e32 v31, 0xffff0000, v0
	v_mul_f32_e32 v0, v32, v32
	v_and_b32_e32 v35, 0xffff0000, v1
	v_mul_f32_e32 v1, v36, v36
	v_lshlrev_b32_e32 v39, 16, v2
	v_lshlrev_b32_e32 v26, 16, v4
	v_fmac_f32_e32 v0, v31, v31
	v_lshlrev_b32_e32 v28, 16, v5
	v_fmac_f32_e32 v1, v35, v35
	v_and_b32_e32 v38, 0xffff0000, v2
	v_mul_f32_e32 v2, v39, v39
	v_and_b32_e32 v17, 0xffff0000, v4
	v_mul_f32_e32 v4, v26, v26
	v_and_b32_e32 v27, 0xffff0000, v5
	v_add_f32_e32 v0, v0, v1
	v_mul_f32_e32 v1, v28, v28
	v_lshlrev_b32_e32 v30, 16, v6
	v_fmac_f32_e32 v2, v38, v38
	v_fmac_f32_e32 v4, v17, v17
	v_fmac_f32_e32 v1, v27, v27
	v_and_b32_e32 v29, 0xffff0000, v6
	v_add_f32_e32 v0, v2, v0
	v_mul_f32_e32 v2, v30, v30
	v_add_f32_e32 v1, v4, v1
	v_fmac_f32_e32 v2, v29, v29
	v_lshlrev_b32_e32 v40, 16, v3
	v_add_f32_e32 v1, v2, v1
	v_and_b32_e32 v37, 0xffff0000, v3
	v_mul_f32_e32 v2, v40, v40
	v_lshlrev_b32_e32 v34, 16, v7
	v_fmac_f32_e32 v2, v37, v37
	v_and_b32_e32 v33, 0xffff0000, v7
	v_add_f32_e32 v0, v2, v0
	v_mul_f32_e32 v2, v34, v34
	v_fmac_f32_e32 v2, v33, v33
	v_add_f32_e32 v1, v2, v1
	s_nop 1
	v_mov_b32_dpp v2, v0 quad_perm:[1,0,3,2] row_mask:0xf bank_mask:0xf
	s_waitcnt lgkmcnt(0)
	v_add_f32_e32 v0, v0, v2
	s_nop 1
	v_mov_b32_dpp v2, v0 quad_perm:[2,3,0,1] row_mask:0xf bank_mask:0xf
	s_waitcnt lgkmcnt(0)
	v_add_f32_e32 v0, v0, v2
	s_nop 1
	v_mov_b32_dpp v2, v0 row_half_mirror row_mask:0xf bank_mask:0xf
	s_waitcnt lgkmcnt(0)
	v_add_f32_e32 v0, v0, v2
	s_nop 1
	v_mov_b32_dpp v2, v0 row_mirror row_mask:0xf bank_mask:0xf
	s_waitcnt lgkmcnt(0)
	v_add_f32_e32 v0, v0, v2
	v_mov_b32_e32 v2, v0
	s_nop 1
	v_permlane16_swap_b32_e32 v0, v2
	s_waitcnt lgkmcnt(0)
	v_add_f32_e32 v0, v0, v2
	v_mov_b32_e32 v2, v0
	s_nop 1
	v_permlane32_swap_b32_e32 v0, v2
	v_add_f32_e32 v0, v0, v2
	v_fmamk_f32 v0, v0, 0x3b000000, v250
	v_cmp_gt_f32_e32 vcc, s12, v0
	v_mul_f32_e32 v2, 0x4f800000, v0
	s_nop 0
	v_cndmask_b32_e32 v0, v0, v2, vcc
	v_sqrt_f32_e32 v2, v0
	s_nop 0
	v_add_u32_e32 v3, -1, v2
	v_fma_f32 v4, -v3, v2, v0
	v_cmp_ge_f32_e64 s[0:1], 0, v4
	v_add_u32_e32 v4, 1, v2
	s_nop 0
	v_cndmask_b32_e64 v3, v2, v3, s[0:1]
	v_fma_f32 v2, -v4, v2, v0
	v_cmp_lt_f32_e64 s[0:1], 0, v2
	s_nop 1
	v_cndmask_b32_e64 v2, v3, v4, s[0:1]
	v_mul_f32_e32 v3, 0x37800000, v2
	v_cndmask_b32_e32 v2, v2, v3, vcc
	v_cmp_class_f32_e32 vcc, v0, v251
	s_nop 1
	v_cndmask_b32_e32 v0, v2, v0, vcc
	v_div_scale_f32 v2, s[0:1], v0, v0, 1.0
	v_rcp_f32_e32 v3, v2
	s_nop 0
	v_fma_f32 v4, -v2, v3, 1.0
	v_fmac_f32_e32 v3, v4, v3
	v_div_scale_f32 v4, vcc, 1.0, v0, 1.0
	v_mul_f32_e32 v5, v4, v3
	v_fma_f32 v6, -v2, v5, v4
	v_fmac_f32_e32 v5, v6, v3
	v_fma_f32 v2, -v2, v5, v4
	v_div_fmas_f32 v2, v2, v3, v5
	v_div_fixup_f32 v41, v2, v0, 1.0
	s_nop 1
	v_mov_b32_dpp v0, v1 quad_perm:[1,0,3,2] row_mask:0xf bank_mask:0xf
	v_mul_f32_e32 v32, v41, v32
	v_mul_f32_e32 v31, v41, v31
	s_waitcnt lgkmcnt(0)
	v_add_f32_e32 v0, v1, v0
	s_nop 1
	v_mov_b32_dpp v1, v0 quad_perm:[2,3,0,1] row_mask:0xf bank_mask:0xf
	s_waitcnt lgkmcnt(0)
	v_add_f32_e32 v0, v0, v1
	s_nop 1
	v_mov_b32_dpp v1, v0 row_half_mirror row_mask:0xf bank_mask:0xf
	s_waitcnt lgkmcnt(0)
	v_add_f32_e32 v0, v0, v1
	s_nop 1
	v_mov_b32_dpp v1, v0 row_mirror row_mask:0xf bank_mask:0xf
	s_waitcnt lgkmcnt(0)
	v_add_f32_e32 v0, v0, v1
	v_mov_b32_e32 v1, v0
	s_nop 1
	v_permlane16_swap_b32_e32 v0, v1
	s_waitcnt lgkmcnt(0)
	v_add_f32_e32 v0, v0, v1
	v_mov_b32_e32 v1, v0
	s_nop 1
	v_permlane32_swap_b32_e32 v0, v1
	v_add_f32_e32 v0, v0, v1
	v_fmamk_f32 v0, v0, 0x3b000000, v250
	v_cmp_gt_f32_e32 vcc, s12, v0
	v_mul_f32_e32 v1, 0x4f800000, v0
	s_nop 0
	v_cndmask_b32_e32 v0, v0, v1, vcc
	v_sqrt_f32_e32 v1, v0
	s_nop 0
	v_add_u32_e32 v2, -1, v1
	v_fma_f32 v3, -v2, v1, v0
	v_cmp_ge_f32_e64 s[0:1], 0, v3
	v_add_u32_e32 v3, 1, v1
	s_nop 0
	v_cndmask_b32_e64 v2, v1, v2, s[0:1]
	v_fma_f32 v1, -v3, v1, v0
	v_cmp_lt_f32_e64 s[0:1], 0, v1
	s_nop 1
	v_cndmask_b32_e64 v1, v2, v3, s[0:1]
	v_mul_f32_e32 v2, 0x37800000, v1
	v_cndmask_b32_e32 v1, v1, v2, vcc
	v_cmp_class_f32_e32 vcc, v0, v251
	s_nop 1
	v_cndmask_b32_e32 v0, v1, v0, vcc
	v_div_scale_f32 v1, s[0:1], v0, v0, 1.0
	v_rcp_f32_e32 v2, v1
	s_nop 0
	v_fma_f32 v3, -v1, v2, 1.0
	v_fmac_f32_e32 v2, v3, v2
	v_div_scale_f32 v3, vcc, 1.0, v0, 1.0
	v_mul_f32_e32 v4, v3, v2
	v_fma_f32 v5, -v1, v4, v3
	v_fmac_f32_e32 v4, v5, v2
	v_fma_f32 v1, -v1, v4, v3
	v_div_fmas_f32 v1, v1, v2, v4
	v_div_fixup_f32 v42, v1, v0, 1.0
	v_mul_f32_e32 v12, v32, v68
	v_mul_f32_e32 v13, v31, v69
	v_cvt_pk_bf16_f32 v12, v12, v13
	v_mul_f32_e32 v13, v41, v36
	v_mul_f32_e32 v13, v13, v70
	v_mul_f32_e32 v14, v41, v35
	v_mul_f32_e32 v14, v14, v71
	v_cvt_pk_bf16_f32 v13, v13, v14
	v_mul_f32_e32 v14, v41, v39
	v_mul_f32_e32 v8, v14, v64
	v_mul_f32_e32 v14, v41, v38
	v_mul_f32_e32 v9, v14, v65
	v_cvt_pk_bf16_f32 v14, v8, v9
	v_mul_f32_e32 v8, v41, v40
	v_mul_f32_e32 v8, v8, v66
	v_mul_f32_e32 v9, v41, v37
	v_mul_f32_e32 v9, v9, v67
	v_cvt_pk_bf16_f32 v15, v8, v9
	v_mul_f32_e32 v8, v42, v26
	v_mul_f32_e32 v4, v76, v8
	v_mul_f32_e32 v8, v42, v17
	v_mul_f32_e32 v5, v77, v8
	v_cvt_pk_bf16_f32 v4, v4, v5
	v_mul_f32_e32 v5, v42, v28
	v_mul_f32_e32 v5, v78, v5
	v_mul_f32_e32 v6, v42, v27
	v_mul_f32_e32 v6, v79, v6
	v_cvt_pk_bf16_f32 v5, v5, v6
	v_mul_f32_e32 v6, v42, v30
	v_mul_f32_e32 v0, v72, v6
	v_mul_f32_e32 v6, v42, v29
	v_mul_f32_e32 v1, v73, v6
	v_cvt_pk_bf16_f32 v6, v0, v1
	v_mul_f32_e32 v0, v42, v34
	v_mul_f32_e32 v1, v42, v33
	v_mul_f32_e32 v0, v74, v0
	v_mul_f32_e32 v1, v75, v1
	v_cvt_pk_bf16_f32 v7, v0, v1
	v_lshl_add_u64 v[0:1], s[38:39], 0, v[24:25]
	v_add_co_u32_e32 v0, vcc, 0x11300000, v0
	s_nop 1
	v_addc_co_u32_e32 v1, vcc, 0, v1, vcc
	global_store_dwordx4 v[0:1], v[12:15], off
	global_store_dwordx4 v[0:1], v[4:7], off offset:1024
	s_and_saveexec_b64 s[0:1], s[34:35]
	s_cbranch_execz .LBB0_355
	v_lshl_add_u64 v[0:1], s[40:41], 0, v[192:193]
	global_load_dword v0, v[0:1], off
	s_cmp_gt_i32 s28, 0x81ff
	s_mov_b64 s[42:43], -1
	s_cbranch_scc0 .LBB0_359
	s_add_i32 s10, s28, 0x7e00
	s_and_b32 s11, s10, 0xffff
	s_mul_i32 s11, s11, 0xf83f
	s_lshr_b32 s11, s11, 28
	s_mulk_i32 s11, 0x1080
	s_sub_i32 s10, s10, s11
	s_and_b32 s10, s10, 0xffff
	s_mov_b64 s[42:43], 0

; __device__ __forceinline__ float bf_lo(unsigned w) { return __uint_as_float(w << 16); }
; __device__ __forceinline__ float bf_hi(unsigned w) { return __uint_as_float(w & 0xffff0000u); }
; template <int X> __device__ __forceinline__ float swz_xor(float v) { return __int_as_float(__builtin_amdgcn_ds_swizzle(__float_as_int(v), 0x1F | (X << 10))); }
; __device__ __forceinline__ float wave_sum(float v) {
;     v += swz_xor<1>(v); v += swz_xor<2>(v); v += swz_xor<4>(v); v += swz_xor<8>(v); v += swz_xor<16>(v);
;     const auto rr = __builtin_amdgcn_permlane32_swap(__float_as_uint(v), __float_as_uint(v), false, false);
;     return __uint_as_float(rr[0]) + __uint_as_float(rr[1]);
; }
; __device__ __forceinline__ void ret_combine_phase(const Frame& F, const bf16_t* OF, const bf16_t* OB, const bf16_t* Gt, bf16_t* U, int rows) {
;     ...
;         for (int k = 0; k < 4; ++k) { const int it = it0 + k * F.NGW; if (it < nitems) { const size_t off = (size_t)it * 512 + F.lane * 8;
;             float o[8]; float s = 0.f;
; #pragma unroll
;             for (int e = 0; e < 4; ++e) { o[2 * e] = bf_lo(a[k][e]) + bf_lo(b[k][e]); o[2 * e + 1] = bf_hi(a[k][e]) + bf_hi(b[k][e]); s += o[2 * e] + o[2 * e + 1]; }
;             const float mu = wave_sum(s) * (1.f / 512.f); float q = 0.f;
; #pragma unroll
;             for (int e = 0; e < 8; ++e) { o[e] -= mu; q += o[e] * o[e]; }
;             const float rstd = 1.0f / sqrtf(wave_sum(q) * (1.f / 512.f) + NORM_EPS);
.LBB0_1149:
	s_waitcnt vmcnt(0)
	v_lshlrev_b32_e32 v49, 16, v44
	v_lshlrev_b32_e32 v52, 16, v40
	v_and_b32_e32 v40, 0xffff0000, v40
	v_and_b32_e32 v44, 0xffff0000, v44
	v_add_f32_e32 v49, v52, v49
	v_add_f32_e32 v52, v40, v44
	v_lshlrev_b32_e32 v44, 16, v45
	v_lshlrev_b32_e32 v53, 16, v41
	v_add_f32_e32 v53, v53, v44
	v_and_b32_e32 v41, 0xffff0000, v41
	v_and_b32_e32 v44, 0xffff0000, v45
	v_add_f32_e32 v40, v52, v49
	v_add_f32_e32 v54, v41, v44
	v_add_f32_e32 v40, 0, v40
	v_add_f32_e32 v41, v54, v53
	v_add_f32_e32 v40, v41, v40
	v_lshlrev_b32_e32 v41, 16, v46
	v_lshlrev_b32_e32 v44, 16, v42
	v_add_f32_e32 v44, v44, v41
	v_and_b32_e32 v41, 0xffff0000, v42
	v_and_b32_e32 v42, 0xffff0000, v46
	v_add_f32_e32 v45, v41, v42
	v_add_f32_e32 v41, v45, v44
	v_add_f32_e32 v42, v41, v40
	v_lshlrev_b32_e32 v40, 16, v47
	v_lshlrev_b32_e32 v41, 16, v43
	v_add_f32_e32 v40, v41, v40
	v_and_b32_e32 v41, 0xffff0000, v43
	v_and_b32_e32 v43, 0xffff0000, v47
	v_add_f32_e32 v41, v41, v43
	v_add_f32_e32 v43, v41, v40
	v_add_f32_e32 v42, v43, v42
	s_nop 1
	v_mov_b32_dpp v43, v42 quad_perm:[1,0,3,2] row_mask:0xf bank_mask:0xf
	s_waitcnt lgkmcnt(0)
	v_add_f32_e32 v42, v42, v43
	s_nop 1
	v_mov_b32_dpp v43, v42 quad_perm:[2,3,0,1] row_mask:0xf bank_mask:0xf
	s_waitcnt lgkmcnt(0)
	v_add_f32_e32 v42, v42, v43
	s_nop 1
	v_mov_b32_dpp v43, v42 row_half_mirror row_mask:0xf bank_mask:0xf
	s_waitcnt lgkmcnt(0)
	v_add_f32_e32 v42, v42, v43
	s_nop 1
	v_mov_b32_dpp v43, v42 row_mirror row_mask:0xf bank_mask:0xf
	s_waitcnt lgkmcnt(0)
	v_add_f32_e32 v42, v42, v43
	v_mov_b32_e32 v43, v42
	s_nop 1
	v_permlane16_swap_b32_e32 v42, v43
	s_waitcnt lgkmcnt(0)
	v_add_f32_e32 v42, v42, v43
	v_mov_b32_e32 v43, v42
	s_nop 1
	v_permlane32_swap_b32_e32 v42, v43
	v_add_f32_e32 v42, v42, v43
	v_fmac_f32_e32 v52, 0xbb000000, v42
	v_fmac_f32_e32 v49, 0xbb000000, v42
	v_mul_f32_e32 v43, v52, v52
	v_fmac_f32_e32 v43, v49, v49
	v_fmac_f32_e32 v53, 0xbb000000, v42
	v_fmac_f32_e32 v43, v53, v53
	v_fmac_f32_e32 v54, 0xbb000000, v42
	v_fmac_f32_e32 v43, v54, v54
	v_fmac_f32_e32 v44, 0xbb000000, v42
	v_fmac_f32_e32 v43, v44, v44
	v_fmac_f32_e32 v45, 0xbb000000, v42
	v_fmac_f32_e32 v43, v45, v45
	v_fmac_f32_e32 v40, 0xbb000000, v42
	v_fmac_f32_e32 v43, v40, v40
	v_fmac_f32_e32 v41, 0xbb000000, v42
	v_fmac_f32_e32 v43, v41, v41
	s_nop 1
	v_mov_b32_dpp v42, v43 quad_perm:[1,0,3,2] row_mask:0xf bank_mask:0xf
	s_waitcnt lgkmcnt(0)
	v_add_f32_e32 v42, v43, v42
	s_nop 1
	v_mov_b32_dpp v43, v42 quad_perm:[2,3,0,1] row_mask:0xf bank_mask:0xf
	s_waitcnt lgkmcnt(0)
	v_add_f32_e32 v42, v42, v43
	s_nop 1
	v_mov_b32_dpp v43, v42 row_half_mirror row_mask:0xf bank_mask:0xf
	s_waitcnt lgkmcnt(0)
	v_add_f32_e32 v42, v42, v43
	s_nop 1
	v_mov_b32_dpp v43, v42 row_mirror row_mask:0xf bank_mask:0xf
	s_waitcnt lgkmcnt(0)
	v_add_f32_e32 v42, v42, v43
	v_mov_b32_e32 v43, v42
	s_nop 1
	v_permlane16_swap_b32_e32 v42, v43
	s_waitcnt lgkmcnt(0)
; #define GAS __attribute__((address_space(1)))
; __device__ __forceinline__ unsigned cvt_pk_bf16(float lo, float hi) { unsigned r; asm volatile("v_cvt_pk_bf16_f32 %0, %1, %2" : "=v"(r) : "v"(lo), "v"(hi)); return r; }
; __device__ __forceinline__ float bf_lo(unsigned w) { return __uint_as_float(w << 16); }
; __device__ __forceinline__ float bf_hi(unsigned w) { return __uint_as_float(w & 0xffff0000u); }
; __device__ __forceinline__ void ret_combine_phase(const Frame& F, const bf16_t* OF, const bf16_t* OB, const bf16_t* Gt, bf16_t* U, int rows) {
;     ...
;             const float rstd = 1.0f / sqrtf(wave_sum(q) * (1.f / 512.f) + NORM_EPS);
;             u32x4 w;
; #pragma unroll
;             for (int e = 0; e < 4; ++e) { const float g0 = bf_lo(g[k][e]), g1 = bf_hi(g[k][e]);
;                 const float y0 = o[2 * e] * rstd, y1 = o[2 * e + 1] * rstd;
;                 const float s0 = g0 / (1.f + __expf(-g0)), s1 = g1 / (1.f + __expf(-g1));
;                 w[e] = cvt_pk_bf16(s0 * y0, s1 * y1); }
;             *(GAS u32x4*)(U + off) = w; } }
	v_add_f32_e32 v42, v42, v43
	v_mov_b32_e32 v43, v42
	s_nop 1
	v_permlane32_swap_b32_e32 v42, v43
	v_add_f32_e32 v42, v42, v43
	v_fmamk_f32 v42, v42, 0x3b000000, v250
	v_cmp_gt_f32_e32 vcc, s11, v42
	v_mul_f32_e32 v43, 0x4f800000, v42
	s_nop 0
	v_cndmask_b32_e32 v42, v42, v43, vcc
	v_sqrt_f32_e32 v43, v42
	s_nop 0
	v_add_u32_e32 v46, -1, v43
	v_fma_f32 v47, -v46, v43, v42
	v_cmp_ge_f32_e64 s[0:1], 0, v47
	v_add_u32_e32 v47, 1, v43
	s_nop 0
	v_cndmask_b32_e64 v46, v43, v46, s[0:1]
	v_fma_f32 v43, -v47, v43, v42
	v_cmp_lt_f32_e64 s[0:1], 0, v43
	s_nop 1
	v_cndmask_b32_e64 v43, v46, v47, s[0:1]
	v_mul_f32_e32 v46, 0x37800000, v43
	v_cndmask_b32_e32 v43, v43, v46, vcc
	v_cmp_class_f32_e32 vcc, v42, v251
	s_nop 1
	v_cndmask_b32_e32 v42, v43, v42, vcc
	v_div_scale_f32 v43, s[0:1], v42, v42, 1.0
	v_rcp_f32_e32 v46, v43
	s_nop 0
	v_fma_f32 v47, -v43, v46, 1.0
	v_fmac_f32_e32 v46, v47, v46
	v_div_scale_f32 v47, vcc, 1.0, v42, 1.0
	v_mul_f32_e32 v55, v47, v46
	v_fma_f32 v56, -v43, v55, v47
	v_fmac_f32_e32 v55, v56, v46
	v_fma_f32 v43, -v43, v55, v47
	v_div_fmas_f32 v43, v43, v46, v55
	v_div_fixup_f32 v42, v43, v42, 1.0
	v_lshlrev_b32_e32 v43, 16, v36
	v_mul_f32_e32 v46, v49, v42
	v_mul_f32_e32 v49, 0xbfb8aa3b, v43
	v_exp_f32_e32 v49, v49
	v_mul_f32_e32 v47, v52, v42
	v_and_b32_e32 v36, 0xffff0000, v36
	v_mul_f32_e32 v44, v44, v42
	v_add_f32_e32 v49, 1.0, v49
	v_div_scale_f32 v52, s[0:1], v49, v49, v43
	v_rcp_f32_e32 v55, v52
	v_mul_f32_e32 v45, v45, v42
	v_mul_f32_e32 v40, v40, v42
	v_mul_f32_e32 v41, v41, v42
	v_fma_f32 v56, -v52, v55, 1.0
	v_fmac_f32_e32 v55, v56, v55
	v_div_scale_f32 v56, vcc, v43, v49, v43
	v_mul_f32_e32 v57, v56, v55
	v_fma_f32 v58, -v52, v57, v56
	v_fmac_f32_e32 v57, v58, v55
	v_fma_f32 v52, -v52, v57, v56
	v_div_fmas_f32 v52, v52, v55, v57
	v_div_fixup_f32 v43, v52, v49, v43
	v_mul_f32_e32 v49, 0xbfb8aa3b, v36
	v_exp_f32_e32 v49, v49
	v_mul_f32_e32 v43, v43, v46
	v_mul_f32_e32 v46, v53, v42
	v_add_f32_e32 v49, 1.0, v49
	v_div_scale_f32 v52, s[0:1], v49, v49, v36
	v_rcp_f32_e32 v55, v52
	s_nop 0
	v_fma_f32 v56, -v52, v55, 1.0
	v_fmac_f32_e32 v55, v56, v55
	v_div_scale_f32 v56, vcc, v36, v49, v36
	v_mul_f32_e32 v57, v56, v55
	v_fma_f32 v58, -v52, v57, v56
	v_fmac_f32_e32 v57, v58, v55
	v_fma_f32 v52, -v52, v57, v56
	v_div_fmas_f32 v52, v52, v55, v57
	v_div_fixup_f32 v36, v52, v49, v36
	v_mul_f32_e32 v36, v36, v47
	v_cvt_pk_bf16_f32 v36, v43, v36
	v_lshlrev_b32_e32 v43, 16, v37
	v_mul_f32_e32 v49, 0xbfb8aa3b, v43
	v_exp_f32_e32 v49, v49
	v_mul_f32_e32 v47, v54, v42
	v_and_b32_e32 v37, 0xffff0000, v37
	v_add_f32_e32 v49, 1.0, v49
	v_div_scale_f32 v52, s[0:1], v49, v49, v43
	v_rcp_f32_e32 v53, v52
	s_nop 0
	v_fma_f32 v54, -v52, v53, 1.0
	v_fmac_f32_e32 v53, v54, v53
	v_div_scale_f32 v54, vcc, v43, v49, v43
	v_mul_f32_e32 v55, v54, v53
	v_fma_f32 v56, -v52, v55, v54
	v_fmac_f32_e32 v55, v56, v53
	v_fma_f32 v52, -v52, v55, v54
	v_div_fmas_f32 v52, v52, v53, v55
	v_div_fixup_f32 v43, v52, v49, v43
	v_mul_f32_e32 v49, 0xbfb8aa3b, v37
	v_exp_f32_e32 v49, v49
	v_mul_f32_e32 v43, v43, v46
	v_add_f32_e32 v49, 1.0, v49
	v_div_scale_f32 v52, s[0:1], v49, v49, v37
	v_rcp_f32_e32 v53, v52
	s_nop 0
	v_fma_f32 v54, -v52, v53, 1.0
	v_fmac_f32_e32 v53, v54, v53
	v_div_scale_f32 v54, vcc, v37, v49, v37
	v_mul_f32_e32 v55, v54, v53
	v_fma_f32 v56, -v52, v55, v54
	v_fmac_f32_e32 v55, v56, v53
	v_fma_f32 v52, -v52, v55, v54
	v_div_fmas_f32 v52, v52, v53, v55
	v_div_fixup_f32 v37, v52, v49, v37
	v_mul_f32_e32 v37, v37, v47
	v_cvt_pk_bf16_f32 v37, v43, v37
	v_lshlrev_b32_e32 v43, 16, v38
	v_mul_f32_e32 v46, 0xbfb8aa3b, v43
	v_exp_f32_e32 v46, v46
	v_and_b32_e32 v38, 0xffff0000, v38
	v_add_f32_e32 v46, 1.0, v46
	v_div_scale_f32 v47, s[0:1], v46, v46, v43
	v_rcp_f32_e32 v49, v47
	s_nop 0
	v_fma_f32 v52, -v47, v49, 1.0
	v_fmac_f32_e32 v49, v52, v49
	v_div_scale_f32 v52, vcc, v43, v46, v43
	v_mul_f32_e32 v53, v52, v49
	v_fma_f32 v54, -v47, v53, v52
	v_fmac_f32_e32 v53, v54, v49
	v_fma_f32 v47, -v47, v53, v52
	v_div_fmas_f32 v47, v47, v49, v53
	v_div_fixup_f32 v43, v47, v46, v43
	v_mul_f32_e32 v46, 0xbfb8aa3b, v38
	v_exp_f32_e32 v46, v46
	v_mul_f32_e32 v43, v43, v44
	v_add_f32_e32 v46, 1.0, v46
	v_div_scale_f32 v47, s[0:1], v46, v46, v38
	v_rcp_f32_e32 v49, v47
	s_nop 0
	v_fma_f32 v52, -v47, v49, 1.0
	v_fmac_f32_e32 v49, v52, v49
	v_div_scale_f32 v52, vcc, v38, v46, v38
	v_mul_f32_e32 v53, v52, v49
	v_fma_f32 v54, -v47, v53, v52
	v_fmac_f32_e32 v53, v54, v49
	v_fma_f32 v47, -v47, v53, v52
	v_div_fmas_f32 v47, v47, v49, v53
	v_div_fixup_f32 v38, v47, v46, v38
	v_mul_f32_e32 v38, v38, v45
	v_cvt_pk_bf16_f32 v38, v43, v38
	v_lshlrev_b32_e32 v43, 16, v39
	v_mul_f32_e32 v42, 0xbfb8aa3b, v43
	v_exp_f32_e32 v42, v42
	v_and_b32_e32 v39, 0xffff0000, v39
	v_add_f32_e32 v42, 1.0, v42
	v_div_scale_f32 v44, s[0:1], v42, v42, v43
	v_rcp_f32_e32 v45, v44
	s_nop 0
	v_fma_f32 v46, -v44, v45, 1.0
	v_fmac_f32_e32 v45, v46, v45
	v_div_scale_f32 v46, vcc, v43, v42, v43
	v_mul_f32_e32 v47, v46, v45
	v_fma_f32 v49, -v44, v47, v46
	v_fmac_f32_e32 v47, v49, v45
	v_fma_f32 v44, -v44, v47, v46
	v_div_fmas_f32 v44, v44, v45, v47
	v_div_fixup_f32 v42, v44, v42, v43
	v_mul_f32_e32 v43, 0xbfb8aa3b, v39
	v_exp_f32_e32 v43, v43
	v_mul_f32_e32 v40, v42, v40
	v_add_f32_e32 v43, 1.0, v43
	v_div_scale_f32 v44, s[0:1], v43, v43, v39
	v_rcp_f32_e32 v45, v44
	s_nop 0
	v_fma_f32 v46, -v44, v45, 1.0
	v_fmac_f32_e32 v45, v46, v45
	v_div_scale_f32 v46, vcc, v39, v43, v39
	v_mul_f32_e32 v47, v46, v45
	v_fma_f32 v49, -v44, v47, v46
	v_fmac_f32_e32 v47, v49, v45
	v_fma_f32 v44, -v44, v47, v46
	v_div_fmas_f32 v44, v44, v45, v47
	v_div_fixup_f32 v39, v44, v43, v39
	v_mul_f32_e32 v39, v39, v41
	v_cvt_pk_bf16_f32 v39, v40, v39
	v_lshl_add_u64 v[40:41], v[50:51], 0, s[48:49]
	s_andn2_b64 vcc, exec, s[50:51]
	global_store_dwordx4 v[40:41], v[36:39], off
	s_cbranch_vccz .LBB0_1152
	s_andn2_b64 vcc, exec, s[46:47]
	s_cbranch_vccz .LBB0_1153

; #define GAS __attribute__((address_space(1)))
; __device__ __forceinline__ unsigned cvt_pk_bf16(float lo, float hi) { unsigned r; asm volatile("v_cvt_pk_bf16_f32 %0, %1, %2" : "=v"(r) : "v"(lo), "v"(hi)); return r; }
; __device__ __forceinline__ float bf_lo(unsigned w) { return __uint_as_float(w << 16); }
; __device__ __forceinline__ float bf_hi(unsigned w) { return __uint_as_float(w & 0xffff0000u); }
; __device__ __forceinline__ void ret_combine_phase(const Frame& F, const bf16_t* OF, const bf16_t* OB, const bf16_t* Gt, bf16_t* U, int rows) {
;     ...
;         for (int k = 0; k < 4; ++k) { const int it = it0 + k * F.NGW; if (it < nitems) { const size_t off = (size_t)it * 512 + F.lane * 8;
;             float o[8]; float s = 0.f;
; #pragma unroll
;             for (int e = 0; e < 4; ++e) { o[2 * e] = bf_lo(a[k][e]) + bf_lo(b[k][e]); o[2 * e + 1] = bf_hi(a[k][e]) + bf_hi(b[k][e]); s += o[2 * e] + o[2 * e + 1]; }
;             const float mu = wave_sum(s) * (1.f / 512.f); float q = 0.f;
; #pragma unroll
;             for (int e = 0; e < 8; ++e) { o[e] -= mu; q += o[e] * o[e]; }
;             const float rstd = 1.0f / sqrtf(wave_sum(q) * (1.f / 512.f) + NORM_EPS);
;             u32x4 w;
; #pragma unroll
;             for (int e = 0; e < 4; ++e) { const float g0 = bf_lo(g[k][e]), g1 = bf_hi(g[k][e]);
;                 const float y0 = o[2 * e] * rstd, y1 = o[2 * e + 1] * rstd;
;                 const float s0 = g0 / (1.f + __expf(-g0)), s1 = g1 / (1.f + __expf(-g1));
;                 w[e] = cvt_pk_bf16(s0 * y0, s1 * y1); }
;             *(GAS u32x4*)(U + off) = w; } }
.LBB0_1152:
	s_nop 0
	v_lshlrev_b32_e32 v36, 16, v12
	v_lshlrev_b32_e32 v37, 16, v0
	v_add_f32_e32 v36, v37, v36
	v_and_b32_e32 v37, 0xffff0000, v0
	v_and_b32_e32 v38, 0xffff0000, v12
	v_lshlrev_b32_e32 v39, 16, v13
	v_lshlrev_b32_e32 v40, 16, v1
	v_add_f32_e32 v37, v37, v38
	v_add_f32_e32 v43, v40, v39
	v_and_b32_e32 v39, 0xffff0000, v1
	v_and_b32_e32 v40, 0xffff0000, v13
	v_add_f32_e32 v38, v37, v36
	v_add_f32_e32 v44, v39, v40
	v_add_f32_e32 v38, 0, v38
	v_add_f32_e32 v39, v44, v43
	v_add_f32_e32 v39, v39, v38
	v_lshlrev_b32_e32 v38, 16, v14
	v_lshlrev_b32_e32 v40, 16, v2
	v_add_f32_e32 v38, v40, v38
	v_and_b32_e32 v40, 0xffff0000, v2
	v_and_b32_e32 v41, 0xffff0000, v14
	v_add_f32_e32 v42, v40, v41
	v_add_f32_e32 v40, v42, v38
	v_add_f32_e32 v41, v40, v39
	v_lshlrev_b32_e32 v39, 16, v15
	v_lshlrev_b32_e32 v40, 16, v3
	v_add_f32_e32 v39, v40, v39
	v_and_b32_e32 v40, 0xffff0000, v3
	v_and_b32_e32 v45, 0xffff0000, v15
	v_add_f32_e32 v40, v40, v45
	v_add_f32_e32 v45, v40, v39
	v_add_f32_e32 v41, v45, v41
	s_nop 1
	v_mov_b32_dpp v45, v41 quad_perm:[1,0,3,2] row_mask:0xf bank_mask:0xf
	s_ashr_i32 s39, s38, 31
	s_waitcnt lgkmcnt(0)
	v_add_f32_e32 v41, v41, v45
	s_nop 1
	v_mov_b32_dpp v45, v41 quad_perm:[2,3,0,1] row_mask:0xf bank_mask:0xf
	s_waitcnt lgkmcnt(0)
	v_add_f32_e32 v41, v41, v45
	s_nop 1
	v_mov_b32_dpp v45, v41 row_half_mirror row_mask:0xf bank_mask:0xf
	s_waitcnt lgkmcnt(0)
	v_add_f32_e32 v41, v41, v45
	s_nop 1
	v_mov_b32_dpp v45, v41 row_mirror row_mask:0xf bank_mask:0xf
	s_waitcnt lgkmcnt(0)
	v_add_f32_e32 v41, v41, v45
	v_mov_b32_e32 v45, v41
	s_nop 1
	v_permlane16_swap_b32_e32 v41, v45
	s_waitcnt lgkmcnt(0)
	v_add_f32_e32 v41, v41, v45
	v_mov_b32_e32 v45, v41
	s_nop 1
	v_permlane32_swap_b32_e32 v41, v45
	v_add_f32_e32 v41, v41, v45
	v_fmac_f32_e32 v37, 0xbb000000, v41
	v_fmac_f32_e32 v36, 0xbb000000, v41
	v_mul_f32_e32 v45, v37, v37
	v_fmac_f32_e32 v45, v36, v36
	v_fmac_f32_e32 v43, 0xbb000000, v41
	v_fmac_f32_e32 v45, v43, v43
	v_fmac_f32_e32 v44, 0xbb000000, v41
	v_fmac_f32_e32 v45, v44, v44
	v_fmac_f32_e32 v38, 0xbb000000, v41
	v_fmac_f32_e32 v45, v38, v38
	v_fmac_f32_e32 v42, 0xbb000000, v41
	v_fmac_f32_e32 v45, v42, v42
	v_fmac_f32_e32 v39, 0xbb000000, v41
	v_fmac_f32_e32 v45, v39, v39
	v_fmac_f32_e32 v40, 0xbb000000, v41
	v_fmac_f32_e32 v45, v40, v40
	s_nop 1
	v_mov_b32_dpp v41, v45 quad_perm:[1,0,3,2] row_mask:0xf bank_mask:0xf
	s_waitcnt lgkmcnt(0)
	v_add_f32_e32 v41, v45, v41
	s_nop 1
	v_mov_b32_dpp v45, v41 quad_perm:[2,3,0,1] row_mask:0xf bank_mask:0xf
	s_waitcnt lgkmcnt(0)
	v_add_f32_e32 v41, v41, v45
	s_nop 1
	v_mov_b32_dpp v45, v41 row_half_mirror row_mask:0xf bank_mask:0xf
	s_waitcnt lgkmcnt(0)
	v_add_f32_e32 v41, v41, v45
	s_nop 1
	v_mov_b32_dpp v45, v41 row_mirror row_mask:0xf bank_mask:0xf
	s_waitcnt lgkmcnt(0)
	v_add_f32_e32 v41, v41, v45
	v_mov_b32_e32 v45, v41
	s_nop 1
	v_permlane16_swap_b32_e32 v41, v45
	s_waitcnt lgkmcnt(0)
	v_add_f32_e32 v41, v41, v45
	v_mov_b32_e32 v45, v41
	s_nop 1
	v_permlane32_swap_b32_e32 v41, v45
	v_add_f32_e32 v41, v41, v45
	v_fmamk_f32 v41, v41, 0x3b000000, v250
	v_cmp_gt_f32_e32 vcc, s11, v41
	v_mul_f32_e32 v45, 0x4f800000, v41
	s_nop 0
	v_cndmask_b32_e32 v41, v41, v45, vcc
	v_sqrt_f32_e32 v45, v41
	s_nop 0
	v_add_u32_e32 v46, -1, v45
	v_fma_f32 v47, -v46, v45, v41
	v_cmp_ge_f32_e64 s[0:1], 0, v47
	v_add_u32_e32 v47, 1, v45
	s_nop 0
	v_cndmask_b32_e64 v46, v45, v46, s[0:1]
	v_fma_f32 v45, -v47, v45, v41
	v_cmp_lt_f32_e64 s[0:1], 0, v45
	s_nop 1
	v_cndmask_b32_e64 v45, v46, v47, s[0:1]
	v_mul_f32_e32 v46, 0x37800000, v45
	v_cndmask_b32_e32 v45, v45, v46, vcc
	v_cmp_class_f32_e32 vcc, v41, v251
	s_nop 1
	v_cndmask_b32_e32 v41, v45, v41, vcc
	v_div_scale_f32 v45, s[0:1], v41, v41, 1.0
	v_rcp_f32_e32 v46, v45
	s_nop 0
	v_fma_f32 v47, -v45, v46, 1.0
	v_fmac_f32_e32 v46, v47, v46
	v_div_scale_f32 v47, vcc, 1.0, v41, 1.0
	v_mul_f32_e32 v49, v47, v46
	v_fma_f32 v52, -v45, v49, v47
	v_fmac_f32_e32 v49, v52, v46
	v_fma_f32 v45, -v45, v49, v47
	v_div_fmas_f32 v45, v45, v46, v49
	v_div_fixup_f32 v41, v45, v41, 1.0
	v_lshlrev_b32_e32 v45, 16, v24
	v_mul_f32_e32 v47, 0xbfb8aa3b, v45
	v_exp_f32_e32 v47, v47
	v_and_b32_e32 v46, 0xffff0000, v24
	v_mul_f32_e32 v36, v36, v41
	v_mul_f32_e32 v37, v37, v41
	v_add_f32_e32 v47, 1.0, v47
	v_div_scale_f32 v49, s[0:1], v47, v47, v45
	v_rcp_f32_e32 v52, v49
	v_mul_f32_e32 v43, v43, v41
	v_mul_f32_e32 v44, v44, v41
	v_mul_f32_e32 v38, v38, v41
	v_fma_f32 v53, -v49, v52, 1.0
	v_fmac_f32_e32 v52, v53, v52
	v_div_scale_f32 v53, vcc, v45, v47, v45
	v_mul_f32_e32 v54, v53, v52
	v_fma_f32 v55, -v49, v54, v53
	v_fmac_f32_e32 v54, v55, v52
	v_fma_f32 v49, -v49, v54, v53
	v_div_fmas_f32 v49, v49, v52, v54
	v_div_fixup_f32 v45, v49, v47, v45
	v_mul_f32_e32 v47, 0xbfb8aa3b, v46
	v_exp_f32_e32 v47, v47
	v_mul_f32_e32 v36, v45, v36
	v_and_b32_e32 v45, 0xffff0000, v25
	v_mul_f32_e32 v42, v42, v41
	v_add_f32_e32 v47, 1.0, v47
	v_div_scale_f32 v49, s[0:1], v47, v47, v46
	v_rcp_f32_e32 v52, v49
	v_mul_f32_e32 v39, v39, v41
	v_mul_f32_e32 v40, v40, v41
	v_fma_f32 v53, -v49, v52, 1.0
	v_fmac_f32_e32 v52, v53, v52
	v_div_scale_f32 v53, vcc, v46, v47, v46
	v_mul_f32_e32 v54, v53, v52
	v_fma_f32 v55, -v49, v54, v53
	v_fmac_f32_e32 v54, v55, v52
	v_fma_f32 v49, -v49, v54, v53
	v_div_fmas_f32 v49, v49, v52, v54
	v_div_fixup_f32 v46, v49, v47, v46
	v_mul_f32_e32 v37, v46, v37
	v_cvt_pk_bf16_f32 v36, v36, v37
	v_lshlrev_b32_e32 v37, 16, v25
	v_mul_f32_e32 v46, 0xbfb8aa3b, v37
	v_exp_f32_e32 v46, v46
	s_nop 0
	v_add_f32_e32 v46, 1.0, v46
	v_div_scale_f32 v47, s[0:1], v46, v46, v37
	v_rcp_f32_e32 v49, v47
	s_nop 0
	v_fma_f32 v52, -v47, v49, 1.0
	v_fmac_f32_e32 v49, v52, v49
; #define GAS __attribute__((address_space(1)))
; __device__ __forceinline__ unsigned cvt_pk_bf16(float lo, float hi) { unsigned r; asm volatile("v_cvt_pk_bf16_f32 %0, %1, %2" : "=v"(r) : "v"(lo), "v"(hi)); return r; }
; __device__ __forceinline__ float bf_lo(unsigned w) { return __uint_as_float(w << 16); }
; __device__ __forceinline__ float bf_hi(unsigned w) { return __uint_as_float(w & 0xffff0000u); }
; __device__ __forceinline__ void ret_combine_phase(const Frame& F, const bf16_t* OF, const bf16_t* OB, const bf16_t* Gt, bf16_t* U, int rows) {
;     ...
; #pragma unroll
;             for (int e = 0; e < 4; ++e) { o[2 * e] = bf_lo(a[k][e]) + bf_lo(b[k][e]); o[2 * e + 1] = bf_hi(a[k][e]) + bf_hi(b[k][e]); s += o[2 * e] + o[2 * e + 1]; }
;             const float mu = wave_sum(s) * (1.f / 512.f); float q = 0.f;
; #pragma unroll
;             for (int e = 0; e < 8; ++e) { o[e] -= mu; q += o[e] * o[e]; }
;             const float rstd = 1.0f / sqrtf(wave_sum(q) * (1.f / 512.f) + NORM_EPS);
;             u32x4 w;
; #pragma unroll
;             for (int e = 0; e < 4; ++e) { const float g0 = bf_lo(g[k][e]), g1 = bf_hi(g[k][e]);
;                 const float y0 = o[2 * e] * rstd, y1 = o[2 * e + 1] * rstd;
;                 const float s0 = g0 / (1.f + __expf(-g0)), s1 = g1 / (1.f + __expf(-g1));
;                 w[e] = cvt_pk_bf16(s0 * y0, s1 * y1); }
;             *(GAS u32x4*)(U + off) = w; } }
	v_div_scale_f32 v52, vcc, v37, v46, v37
	v_mul_f32_e32 v53, v52, v49
	v_fma_f32 v54, -v47, v53, v52
	v_fmac_f32_e32 v53, v54, v49
	v_fma_f32 v47, -v47, v53, v52
	v_div_fmas_f32 v47, v47, v49, v53
	v_div_fixup_f32 v37, v47, v46, v37
	v_mul_f32_e32 v46, 0xbfb8aa3b, v45
	v_exp_f32_e32 v46, v46
	v_mul_f32_e32 v37, v37, v43
	v_add_f32_e32 v46, 1.0, v46
	v_div_scale_f32 v47, s[0:1], v46, v46, v45
	v_rcp_f32_e32 v49, v47
	s_nop 0
	v_fma_f32 v52, -v47, v49, 1.0
	v_fmac_f32_e32 v49, v52, v49
	v_div_scale_f32 v52, vcc, v45, v46, v45
	v_mul_f32_e32 v53, v52, v49
	v_fma_f32 v54, -v47, v53, v52
	v_fmac_f32_e32 v53, v54, v49
	v_fma_f32 v47, -v47, v53, v52
	v_div_fmas_f32 v47, v47, v49, v53
	v_div_fixup_f32 v45, v47, v46, v45
	v_mul_f32_e32 v43, v45, v44
	v_cvt_pk_bf16_f32 v37, v37, v43
	v_lshlrev_b32_e32 v43, 16, v26
	v_mul_f32_e32 v45, 0xbfb8aa3b, v43
	v_exp_f32_e32 v45, v45
	v_and_b32_e32 v44, 0xffff0000, v26
	v_add_f32_e32 v45, 1.0, v45
	v_div_scale_f32 v46, s[0:1], v45, v45, v43
	v_rcp_f32_e32 v47, v46
	s_nop 0
	v_fma_f32 v49, -v46, v47, 1.0
	v_fmac_f32_e32 v47, v49, v47
	v_div_scale_f32 v49, vcc, v43, v45, v43
	v_mul_f32_e32 v52, v49, v47
	v_fma_f32 v53, -v46, v52, v49
	v_fmac_f32_e32 v52, v53, v47
	v_fma_f32 v46, -v46, v52, v49
	v_div_fmas_f32 v46, v46, v47, v52
	v_div_fixup_f32 v43, v46, v45, v43
	v_mul_f32_e32 v45, 0xbfb8aa3b, v44
	v_exp_f32_e32 v45, v45
	v_mul_f32_e32 v38, v43, v38
	v_and_b32_e32 v43, 0xffff0000, v27
	v_add_f32_e32 v45, 1.0, v45
	v_div_scale_f32 v46, s[0:1], v45, v45, v44
	v_rcp_f32_e32 v47, v46
	s_nop 0
	v_fma_f32 v49, -v46, v47, 1.0
	v_fmac_f32_e32 v47, v49, v47
	v_div_scale_f32 v49, vcc, v44, v45, v44
	v_mul_f32_e32 v52, v49, v47
	v_fma_f32 v53, -v46, v52, v49
	v_fmac_f32_e32 v52, v53, v47
	v_fma_f32 v46, -v46, v52, v49
	v_div_fmas_f32 v46, v46, v47, v52
	v_div_fixup_f32 v44, v46, v45, v44
	v_mul_f32_e32 v42, v44, v42
	v_cvt_pk_bf16_f32 v38, v38, v42
	v_lshlrev_b32_e32 v42, 16, v27
	v_mul_f32_e32 v41, 0xbfb8aa3b, v42
	v_exp_f32_e32 v41, v41
	s_nop 0
	v_add_f32_e32 v41, 1.0, v41
	v_div_scale_f32 v44, s[0:1], v41, v41, v42
	v_rcp_f32_e32 v45, v44
	s_nop 0
	v_fma_f32 v46, -v44, v45, 1.0
	v_fmac_f32_e32 v45, v46, v45
	v_div_scale_f32 v46, vcc, v42, v41, v42
	v_mul_f32_e32 v47, v46, v45
	v_fma_f32 v49, -v44, v47, v46
	v_fmac_f32_e32 v47, v49, v45
	v_fma_f32 v44, -v44, v47, v46
	v_div_fmas_f32 v44, v44, v45, v47
	v_div_fixup_f32 v41, v44, v41, v42
	v_mul_f32_e32 v42, 0xbfb8aa3b, v43
	v_exp_f32_e32 v42, v42
	v_mul_f32_e32 v39, v41, v39
	v_add_f32_e32 v42, 1.0, v42
	v_div_scale_f32 v44, s[0:1], v42, v42, v43
	v_rcp_f32_e32 v45, v44
	s_lshl_b64 s[0:1], s[38:39], 10
	v_fma_f32 v46, -v44, v45, 1.0
	v_fmac_f32_e32 v45, v46, v45
	v_div_scale_f32 v46, vcc, v43, v42, v43
	v_mul_f32_e32 v47, v46, v45
	v_fma_f32 v49, -v44, v47, v46
	v_fmac_f32_e32 v47, v49, v45
	v_fma_f32 v44, -v44, v47, v46
	v_div_fmas_f32 v44, v44, v45, v47
	v_div_fixup_f32 v42, v44, v42, v43
	v_mul_f32_e32 v40, v42, v40
	v_cvt_pk_bf16_f32 v39, v39, v40
	v_lshl_add_u64 v[40:41], v[50:51], 0, s[0:1]
	global_store_dwordx4 v[40:41], v[36:39], off
	s_andn2_b64 vcc, exec, s[46:47]
	s_cbranch_vccnz .LBB0_1151
.LBB0_1153:
	v_lshlrev_b32_e32 v36, 16, v8
	v_lshlrev_b32_e32 v37, 16, v28
	v_add_f32_e32 v36, v37, v36
	v_and_b32_e32 v37, 0xffff0000, v28
	v_and_b32_e32 v38, 0xffff0000, v8
	v_lshlrev_b32_e32 v39, 16, v9
	v_lshlrev_b32_e32 v40, 16, v29
	v_add_f32_e32 v37, v37, v38
	v_add_f32_e32 v43, v40, v39
	v_and_b32_e32 v39, 0xffff0000, v29
	v_and_b32_e32 v40, 0xffff0000, v9
	v_add_f32_e32 v38, v37, v36
	v_add_f32_e32 v44, v39, v40
	v_add_f32_e32 v38, 0, v38
	v_add_f32_e32 v39, v44, v43
	v_add_f32_e32 v39, v39, v38
	v_lshlrev_b32_e32 v38, 16, v10
	v_lshlrev_b32_e32 v40, 16, v30
	v_add_f32_e32 v38, v40, v38
	v_and_b32_e32 v40, 0xffff0000, v30
	v_and_b32_e32 v41, 0xffff0000, v10
	v_add_f32_e32 v42, v40, v41
	v_add_f32_e32 v40, v42, v38
	v_add_f32_e32 v41, v40, v39
	v_lshlrev_b32_e32 v39, 16, v11
	v_lshlrev_b32_e32 v40, 16, v31
	v_add_f32_e32 v39, v40, v39
	v_and_b32_e32 v40, 0xffff0000, v31
	v_and_b32_e32 v45, 0xffff0000, v11
	v_add_f32_e32 v40, v40, v45
	v_add_f32_e32 v45, v40, v39
	v_add_f32_e32 v41, v45, v41
	s_nop 1
	v_mov_b32_dpp v45, v41 quad_perm:[1,0,3,2] row_mask:0xf bank_mask:0xf
	s_ashr_i32 s43, s42, 31
	s_waitcnt lgkmcnt(0)
	v_add_f32_e32 v41, v41, v45
	s_nop 1
	v_mov_b32_dpp v45, v41 quad_perm:[2,3,0,1] row_mask:0xf bank_mask:0xf
	s_waitcnt lgkmcnt(0)
	v_add_f32_e32 v41, v41, v45
	s_nop 1
	v_mov_b32_dpp v45, v41 row_half_mirror row_mask:0xf bank_mask:0xf
	s_waitcnt lgkmcnt(0)
	v_add_f32_e32 v41, v41, v45
	s_nop 1
	v_mov_b32_dpp v45, v41 row_mirror row_mask:0xf bank_mask:0xf
	s_waitcnt lgkmcnt(0)
	v_add_f32_e32 v41, v41, v45
	v_mov_b32_e32 v45, v41
	s_nop 1
	v_permlane16_swap_b32_e32 v41, v45
	s_waitcnt lgkmcnt(0)
	v_add_f32_e32 v41, v41, v45
	v_mov_b32_e32 v45, v41
	s_nop 1
	v_permlane32_swap_b32_e32 v41, v45
	v_add_f32_e32 v41, v41, v45
	v_fmac_f32_e32 v37, 0xbb000000, v41
	v_fmac_f32_e32 v36, 0xbb000000, v41
	v_mul_f32_e32 v45, v37, v37
	v_fmac_f32_e32 v45, v36, v36
	v_fmac_f32_e32 v43, 0xbb000000, v41
	v_fmac_f32_e32 v45, v43, v43
	v_fmac_f32_e32 v44, 0xbb000000, v41
	v_fmac_f32_e32 v45, v44, v44
	v_fmac_f32_e32 v38, 0xbb000000, v41
	v_fmac_f32_e32 v45, v38, v38
	v_fmac_f32_e32 v42, 0xbb000000, v41
	v_fmac_f32_e32 v45, v42, v42
	v_fmac_f32_e32 v39, 0xbb000000, v41
	v_fmac_f32_e32 v45, v39, v39
	v_fmac_f32_e32 v40, 0xbb000000, v41
	v_fmac_f32_e32 v45, v40, v40
	s_nop 1
	v_mov_b32_dpp v41, v45 quad_perm:[1,0,3,2] row_mask:0xf bank_mask:0xf
	s_waitcnt lgkmcnt(0)
	v_add_f32_e32 v41, v45, v41
	s_nop 1
	v_mov_b32_dpp v45, v41 quad_perm:[2,3,0,1] row_mask:0xf bank_mask:0xf
	s_waitcnt lgkmcnt(0)
; #define GAS __attribute__((address_space(1)))
; __device__ __forceinline__ unsigned cvt_pk_bf16(float lo, float hi) { unsigned r; asm volatile("v_cvt_pk_bf16_f32 %0, %1, %2" : "=v"(r) : "v"(lo), "v"(hi)); return r; }
; __device__ __forceinline__ float bf_lo(unsigned w) { return __uint_as_float(w << 16); }
; __device__ __forceinline__ float bf_hi(unsigned w) { return __uint_as_float(w & 0xffff0000u); }
; __device__ __forceinline__ void ret_combine_phase(const Frame& F, const bf16_t* OF, const bf16_t* OB, const bf16_t* Gt, bf16_t* U, int rows) {
;     ...
;             const float mu = wave_sum(s) * (1.f / 512.f); float q = 0.f;
; #pragma unroll
;             for (int e = 0; e < 8; ++e) { o[e] -= mu; q += o[e] * o[e]; }
;             const float rstd = 1.0f / sqrtf(wave_sum(q) * (1.f / 512.f) + NORM_EPS);
;             u32x4 w;
; #pragma unroll
;             for (int e = 0; e < 4; ++e) { const float g0 = bf_lo(g[k][e]), g1 = bf_hi(g[k][e]);
;                 const float y0 = o[2 * e] * rstd, y1 = o[2 * e + 1] * rstd;
;                 const float s0 = g0 / (1.f + __expf(-g0)), s1 = g1 / (1.f + __expf(-g1));
;                 w[e] = cvt_pk_bf16(s0 * y0, s1 * y1); }
;             *(GAS u32x4*)(U + off) = w; } }
	v_add_f32_e32 v41, v41, v45
	s_nop 1
	v_mov_b32_dpp v45, v41 row_half_mirror row_mask:0xf bank_mask:0xf
	s_waitcnt lgkmcnt(0)
	v_add_f32_e32 v41, v41, v45
	s_nop 1
	v_mov_b32_dpp v45, v41 row_mirror row_mask:0xf bank_mask:0xf
	s_waitcnt lgkmcnt(0)
	v_add_f32_e32 v41, v41, v45
	v_mov_b32_e32 v45, v41
	s_nop 1
	v_permlane16_swap_b32_e32 v41, v45
	s_waitcnt lgkmcnt(0)
	v_add_f32_e32 v41, v41, v45
	v_mov_b32_e32 v45, v41
	s_nop 1
	v_permlane32_swap_b32_e32 v41, v45
	v_add_f32_e32 v41, v41, v45
	v_fmamk_f32 v41, v41, 0x3b000000, v250
	v_cmp_gt_f32_e32 vcc, s11, v41
	v_mul_f32_e32 v45, 0x4f800000, v41
	s_nop 0
	v_cndmask_b32_e32 v41, v41, v45, vcc
	v_sqrt_f32_e32 v45, v41
	s_nop 0
	v_add_u32_e32 v46, -1, v45
	v_fma_f32 v47, -v46, v45, v41
	v_cmp_ge_f32_e64 s[0:1], 0, v47
	v_add_u32_e32 v47, 1, v45
	s_nop 0
	v_cndmask_b32_e64 v46, v45, v46, s[0:1]
	v_fma_f32 v45, -v47, v45, v41
	v_cmp_lt_f32_e64 s[0:1], 0, v45
	s_nop 1
	v_cndmask_b32_e64 v45, v46, v47, s[0:1]
	v_mul_f32_e32 v46, 0x37800000, v45
	v_cndmask_b32_e32 v45, v45, v46, vcc
	v_cmp_class_f32_e32 vcc, v41, v251
	s_nop 1
	v_cndmask_b32_e32 v41, v45, v41, vcc
	v_div_scale_f32 v45, s[0:1], v41, v41, 1.0
	v_rcp_f32_e32 v46, v45
	s_nop 0
	v_fma_f32 v47, -v45, v46, 1.0
	v_fmac_f32_e32 v46, v47, v46
	v_div_scale_f32 v47, vcc, 1.0, v41, 1.0
	v_mul_f32_e32 v49, v47, v46
	v_fma_f32 v52, -v45, v49, v47
	v_fmac_f32_e32 v49, v52, v46
	v_fma_f32 v45, -v45, v49, v47
	v_div_fmas_f32 v45, v45, v46, v49
	v_div_fixup_f32 v41, v45, v41, 1.0
	v_lshlrev_b32_e32 v45, 16, v20
	v_mul_f32_e32 v47, 0xbfb8aa3b, v45
	v_exp_f32_e32 v47, v47
	v_and_b32_e32 v46, 0xffff0000, v20
	v_mul_f32_e32 v36, v36, v41
	v_mul_f32_e32 v37, v37, v41
	v_add_f32_e32 v47, 1.0, v47
	v_div_scale_f32 v49, s[0:1], v47, v47, v45
	v_rcp_f32_e32 v52, v49
	v_mul_f32_e32 v43, v43, v41
	v_mul_f32_e32 v44, v44, v41
	v_mul_f32_e32 v38, v38, v41
	v_fma_f32 v53, -v49, v52, 1.0
	v_fmac_f32_e32 v52, v53, v52
	v_div_scale_f32 v53, vcc, v45, v47, v45
	v_mul_f32_e32 v54, v53, v52
	v_fma_f32 v55, -v49, v54, v53
	v_fmac_f32_e32 v54, v55, v52
	v_fma_f32 v49, -v49, v54, v53
	v_div_fmas_f32 v49, v49, v52, v54
	v_div_fixup_f32 v45, v49, v47, v45
	v_mul_f32_e32 v47, 0xbfb8aa3b, v46
	v_exp_f32_e32 v47, v47
	v_mul_f32_e32 v36, v45, v36
	v_and_b32_e32 v45, 0xffff0000, v21
	v_mul_f32_e32 v42, v42, v41
	v_add_f32_e32 v47, 1.0, v47
	v_div_scale_f32 v49, s[0:1], v47, v47, v46
	v_rcp_f32_e32 v52, v49
	v_mul_f32_e32 v39, v39, v41
	v_mul_f32_e32 v40, v40, v41
	v_fma_f32 v53, -v49, v52, 1.0
	v_fmac_f32_e32 v52, v53, v52
	v_div_scale_f32 v53, vcc, v46, v47, v46
	v_mul_f32_e32 v54, v53, v52
	v_fma_f32 v55, -v49, v54, v53
	v_fmac_f32_e32 v54, v55, v52
	v_fma_f32 v49, -v49, v54, v53
	v_div_fmas_f32 v49, v49, v52, v54
	v_div_fixup_f32 v46, v49, v47, v46
	v_mul_f32_e32 v37, v46, v37
	v_cvt_pk_bf16_f32 v36, v36, v37
	v_lshlrev_b32_e32 v37, 16, v21
	v_mul_f32_e32 v46, 0xbfb8aa3b, v37
	v_exp_f32_e32 v46, v46
	s_nop 0
	v_add_f32_e32 v46, 1.0, v46
	v_div_scale_f32 v47, s[0:1], v46, v46, v37
	v_rcp_f32_e32 v49, v47
	s_nop 0
	v_fma_f32 v52, -v47, v49, 1.0
	v_fmac_f32_e32 v49, v52, v49
	v_div_scale_f32 v52, vcc, v37, v46, v37
	v_mul_f32_e32 v53, v52, v49
	v_fma_f32 v54, -v47, v53, v52
	v_fmac_f32_e32 v53, v54, v49
	v_fma_f32 v47, -v47, v53, v52
	v_div_fmas_f32 v47, v47, v49, v53
	v_div_fixup_f32 v37, v47, v46, v37
	v_mul_f32_e32 v46, 0xbfb8aa3b, v45
	v_exp_f32_e32 v46, v46
	v_mul_f32_e32 v37, v37, v43
	v_add_f32_e32 v46, 1.0, v46
	v_div_scale_f32 v47, s[0:1], v46, v46, v45
	v_rcp_f32_e32 v49, v47
	s_nop 0
	v_fma_f32 v52, -v47, v49, 1.0
	v_fmac_f32_e32 v49, v52, v49
	v_div_scale_f32 v52, vcc, v45, v46, v45
	v_mul_f32_e32 v53, v52, v49
	v_fma_f32 v54, -v47, v53, v52
	v_fmac_f32_e32 v53, v54, v49
	v_fma_f32 v47, -v47, v53, v52
	v_div_fmas_f32 v47, v47, v49, v53
	v_div_fixup_f32 v45, v47, v46, v45
	v_mul_f32_e32 v43, v45, v44
	v_cvt_pk_bf16_f32 v37, v37, v43
	v_lshlrev_b32_e32 v43, 16, v22
	v_mul_f32_e32 v45, 0xbfb8aa3b, v43
	v_exp_f32_e32 v45, v45
	v_and_b32_e32 v44, 0xffff0000, v22
	v_add_f32_e32 v45, 1.0, v45
	v_div_scale_f32 v46, s[0:1], v45, v45, v43
	v_rcp_f32_e32 v47, v46
	s_nop 0
	v_fma_f32 v49, -v46, v47, 1.0
	v_fmac_f32_e32 v47, v49, v47
	v_div_scale_f32 v49, vcc, v43, v45, v43
	v_mul_f32_e32 v52, v49, v47
	v_fma_f32 v53, -v46, v52, v49
	v_fmac_f32_e32 v52, v53, v47
	v_fma_f32 v46, -v46, v52, v49
	v_div_fmas_f32 v46, v46, v47, v52
	v_div_fixup_f32 v43, v46, v45, v43
	v_mul_f32_e32 v45, 0xbfb8aa3b, v44
	v_exp_f32_e32 v45, v45
	v_mul_f32_e32 v38, v43, v38
	v_and_b32_e32 v43, 0xffff0000, v23
	v_add_f32_e32 v45, 1.0, v45
	v_div_scale_f32 v46, s[0:1], v45, v45, v44
	v_rcp_f32_e32 v47, v46
	s_nop 0
	v_fma_f32 v49, -v46, v47, 1.0
	v_fmac_f32_e32 v47, v49, v47
	v_div_scale_f32 v49, vcc, v44, v45, v44
	v_mul_f32_e32 v52, v49, v47
	v_fma_f32 v53, -v46, v52, v49
	v_fmac_f32_e32 v52, v53, v47
	v_fma_f32 v46, -v46, v52, v49
	v_div_fmas_f32 v46, v46, v47, v52
	v_div_fixup_f32 v44, v46, v45, v44
	v_mul_f32_e32 v42, v44, v42
	v_cvt_pk_bf16_f32 v38, v38, v42
	v_lshlrev_b32_e32 v42, 16, v23
	v_mul_f32_e32 v41, 0xbfb8aa3b, v42
	v_exp_f32_e32 v41, v41
	s_nop 0
	v_add_f32_e32 v41, 1.0, v41
	v_div_scale_f32 v44, s[0:1], v41, v41, v42
	v_rcp_f32_e32 v45, v44
	s_nop 0
	v_fma_f32 v46, -v44, v45, 1.0
	v_fmac_f32_e32 v45, v46, v45
	v_div_scale_f32 v46, vcc, v42, v41, v42
	v_mul_f32_e32 v47, v46, v45
	v_fma_f32 v49, -v44, v47, v46
	v_fmac_f32_e32 v47, v49, v45
	v_fma_f32 v44, -v44, v47, v46
	v_div_fmas_f32 v44, v44, v45, v47
	v_div_fixup_f32 v41, v44, v41, v42
	v_mul_f32_e32 v42, 0xbfb8aa3b, v43
	v_exp_f32_e32 v42, v42
	v_mul_f32_e32 v39, v41, v39
	v_add_f32_e32 v42, 1.0, v42
	v_div_scale_f32 v44, s[0:1], v42, v42, v43
	v_rcp_f32_e32 v45, v44
	s_lshl_b64 s[0:1], s[42:43], 10
	v_fma_f32 v46, -v44, v45, 1.0
	v_fmac_f32_e32 v45, v46, v45
	v_div_scale_f32 v46, vcc, v43, v42, v43
	v_mul_f32_e32 v47, v46, v45
	v_fma_f32 v49, -v44, v47, v46
	v_fmac_f32_e32 v47, v49, v45
	v_fma_f32 v44, -v44, v47, v46
	v_div_fmas_f32 v44, v44, v45, v47
	v_div_fixup_f32 v42, v44, v42, v43
	v_mul_f32_e32 v40, v42, v40
	v_cvt_pk_bf16_f32 v39, v39, v40
	v_lshl_add_u64 v[40:41], v[50:51], 0, s[0:1]
	global_store_dwordx4 v[40:41], v[36:39], off
	s_andn2_b64 vcc, exec, s[44:45]
	s_cbranch_vccnz .LBB0_1142
; __device__ __forceinline__ float bf_lo(unsigned w) { return __uint_as_float(w << 16); }
; __device__ __forceinline__ float bf_hi(unsigned w) { return __uint_as_float(w & 0xffff0000u); }
; template <int X> __device__ __forceinline__ float swz_xor(float v) { return __int_as_float(__builtin_amdgcn_ds_swizzle(__float_as_int(v), 0x1F | (X << 10))); }
; __device__ __forceinline__ float wave_sum(float v) {
;     v += swz_xor<1>(v); v += swz_xor<2>(v); v += swz_xor<4>(v); v += swz_xor<8>(v); v += swz_xor<16>(v);
;     const auto rr = __builtin_amdgcn_permlane32_swap(__float_as_uint(v), __float_as_uint(v), false, false);
;     return __uint_as_float(rr[0]) + __uint_as_float(rr[1]);
; }
; __device__ __forceinline__ void ret_combine_phase(const Frame& F, const bf16_t* OF, const bf16_t* OB, const bf16_t* Gt, bf16_t* U, int rows) {
;     ...
;         for (int k = 0; k < 4; ++k) { const int it = it0 + k * F.NGW; if (it < nitems) { const size_t off = (size_t)it * 512 + F.lane * 8;
;             float o[8]; float s = 0.f;
; #pragma unroll
;             for (int e = 0; e < 4; ++e) { o[2 * e] = bf_lo(a[k][e]) + bf_lo(b[k][e]); o[2 * e + 1] = bf_hi(a[k][e]) + bf_hi(b[k][e]); s += o[2 * e] + o[2 * e + 1]; }
;             const float mu = wave_sum(s) * (1.f / 512.f); float q = 0.f;
; #pragma unroll
;             for (int e = 0; e < 8; ++e) { o[e] -= mu; q += o[e] * o[e]; }
;             const float rstd = 1.0f / sqrtf(wave_sum(q) * (1.f / 512.f) + NORM_EPS);
.LBB0_1154:
	v_lshlrev_b32_e32 v36, 16, v4
	v_lshlrev_b32_e32 v37, 16, v32
	v_add_f32_e32 v36, v37, v36
	v_and_b32_e32 v37, 0xffff0000, v32
	v_and_b32_e32 v38, 0xffff0000, v4
	v_lshlrev_b32_e32 v39, 16, v5
	v_lshlrev_b32_e32 v40, 16, v33
	v_add_f32_e32 v37, v37, v38
	v_add_f32_e32 v43, v40, v39
	v_and_b32_e32 v39, 0xffff0000, v33
	v_and_b32_e32 v40, 0xffff0000, v5
	v_add_f32_e32 v38, v37, v36
	v_add_f32_e32 v44, v39, v40
	v_add_f32_e32 v38, 0, v38
	v_add_f32_e32 v39, v44, v43
	v_add_f32_e32 v39, v39, v38
	v_lshlrev_b32_e32 v38, 16, v6
	v_lshlrev_b32_e32 v40, 16, v34
	v_add_f32_e32 v38, v40, v38
	v_and_b32_e32 v40, 0xffff0000, v34
	v_and_b32_e32 v41, 0xffff0000, v6
	v_add_f32_e32 v42, v40, v41
	v_add_f32_e32 v40, v42, v38
	v_add_f32_e32 v41, v40, v39
	v_lshlrev_b32_e32 v39, 16, v7
	v_lshlrev_b32_e32 v40, 16, v35
	v_add_f32_e32 v39, v40, v39
	v_and_b32_e32 v40, 0xffff0000, v35
	v_and_b32_e32 v45, 0xffff0000, v7
	v_add_f32_e32 v40, v40, v45
	v_add_f32_e32 v45, v40, v39
	v_add_f32_e32 v41, v45, v41
	s_nop 1
	v_mov_b32_dpp v45, v41 quad_perm:[1,0,3,2] row_mask:0xf bank_mask:0xf
	s_ashr_i32 s41, s40, 31
	s_waitcnt lgkmcnt(0)
	v_add_f32_e32 v41, v41, v45
	s_nop 1
	v_mov_b32_dpp v45, v41 quad_perm:[2,3,0,1] row_mask:0xf bank_mask:0xf
	s_waitcnt lgkmcnt(0)
	v_add_f32_e32 v41, v41, v45
	s_nop 1
	v_mov_b32_dpp v45, v41 row_half_mirror row_mask:0xf bank_mask:0xf
	s_waitcnt lgkmcnt(0)
	v_add_f32_e32 v41, v41, v45
	s_nop 1
	v_mov_b32_dpp v45, v41 row_mirror row_mask:0xf bank_mask:0xf
	s_waitcnt lgkmcnt(0)
	v_add_f32_e32 v41, v41, v45
	v_mov_b32_e32 v45, v41
	s_nop 1
	v_permlane16_swap_b32_e32 v41, v45
	s_waitcnt lgkmcnt(0)
	v_add_f32_e32 v41, v41, v45
	v_mov_b32_e32 v45, v41
	s_nop 1
	v_permlane32_swap_b32_e32 v41, v45
	v_add_f32_e32 v41, v41, v45
	v_fmac_f32_e32 v37, 0xbb000000, v41
	v_fmac_f32_e32 v36, 0xbb000000, v41
	v_mul_f32_e32 v45, v37, v37
	v_fmac_f32_e32 v45, v36, v36
	v_fmac_f32_e32 v43, 0xbb000000, v41
	v_fmac_f32_e32 v45, v43, v43
	v_fmac_f32_e32 v44, 0xbb000000, v41
	v_fmac_f32_e32 v45, v44, v44
	v_fmac_f32_e32 v38, 0xbb000000, v41
	v_fmac_f32_e32 v45, v38, v38
	v_fmac_f32_e32 v42, 0xbb000000, v41
	v_fmac_f32_e32 v45, v42, v42
	v_fmac_f32_e32 v39, 0xbb000000, v41
	v_fmac_f32_e32 v45, v39, v39
	v_fmac_f32_e32 v40, 0xbb000000, v41
	v_fmac_f32_e32 v45, v40, v40
	s_nop 1
	v_mov_b32_dpp v41, v45 quad_perm:[1,0,3,2] row_mask:0xf bank_mask:0xf
	s_waitcnt lgkmcnt(0)
	v_add_f32_e32 v41, v45, v41
	s_nop 1
	v_mov_b32_dpp v45, v41 quad_perm:[2,3,0,1] row_mask:0xf bank_mask:0xf
	s_waitcnt lgkmcnt(0)
	v_add_f32_e32 v41, v41, v45
	s_nop 1
	v_mov_b32_dpp v45, v41 row_half_mirror row_mask:0xf bank_mask:0xf
	s_waitcnt lgkmcnt(0)
	v_add_f32_e32 v41, v41, v45
	s_nop 1
	v_mov_b32_dpp v45, v41 row_mirror row_mask:0xf bank_mask:0xf
	s_waitcnt lgkmcnt(0)
	v_add_f32_e32 v41, v41, v45
	v_mov_b32_e32 v45, v41
	s_nop 1
	v_permlane16_swap_b32_e32 v41, v45
	s_waitcnt lgkmcnt(0)
; #define GAS __attribute__((address_space(1)))
; __device__ __forceinline__ unsigned cvt_pk_bf16(float lo, float hi) { unsigned r; asm volatile("v_cvt_pk_bf16_f32 %0, %1, %2" : "=v"(r) : "v"(lo), "v"(hi)); return r; }
; __device__ __forceinline__ float bf_lo(unsigned w) { return __uint_as_float(w << 16); }
; __device__ __forceinline__ float bf_hi(unsigned w) { return __uint_as_float(w & 0xffff0000u); }
; __device__ __forceinline__ void ret_combine_phase(const Frame& F, const bf16_t* OF, const bf16_t* OB, const bf16_t* Gt, bf16_t* U, int rows) {
;     ...
;             const float rstd = 1.0f / sqrtf(wave_sum(q) * (1.f / 512.f) + NORM_EPS);
;             u32x4 w;
; #pragma unroll
;             for (int e = 0; e < 4; ++e) { const float g0 = bf_lo(g[k][e]), g1 = bf_hi(g[k][e]);
;                 const float y0 = o[2 * e] * rstd, y1 = o[2 * e + 1] * rstd;
;                 const float s0 = g0 / (1.f + __expf(-g0)), s1 = g1 / (1.f + __expf(-g1));
;                 w[e] = cvt_pk_bf16(s0 * y0, s1 * y1); }
;             *(GAS u32x4*)(U + off) = w; } }
	v_add_f32_e32 v41, v41, v45
	v_mov_b32_e32 v45, v41
	s_nop 1
	v_permlane32_swap_b32_e32 v41, v45
	v_add_f32_e32 v41, v41, v45
	v_fmamk_f32 v41, v41, 0x3b000000, v250
	v_cmp_gt_f32_e32 vcc, s11, v41
	v_mul_f32_e32 v45, 0x4f800000, v41
	s_nop 0
	v_cndmask_b32_e32 v41, v41, v45, vcc
	v_sqrt_f32_e32 v45, v41
	s_nop 0
	v_add_u32_e32 v46, -1, v45
	v_fma_f32 v47, -v46, v45, v41
	v_cmp_ge_f32_e64 s[0:1], 0, v47
	v_add_u32_e32 v47, 1, v45
	s_nop 0
	v_cndmask_b32_e64 v46, v45, v46, s[0:1]
	v_fma_f32 v45, -v47, v45, v41
	v_cmp_lt_f32_e64 s[0:1], 0, v45
	s_nop 1
	v_cndmask_b32_e64 v45, v46, v47, s[0:1]
	v_mul_f32_e32 v46, 0x37800000, v45
	v_cndmask_b32_e32 v45, v45, v46, vcc
	v_cmp_class_f32_e32 vcc, v41, v251
	s_nop 1
	v_cndmask_b32_e32 v41, v45, v41, vcc
	v_div_scale_f32 v45, s[0:1], v41, v41, 1.0
	v_rcp_f32_e32 v46, v45
	s_nop 0
	v_fma_f32 v47, -v45, v46, 1.0
	v_fmac_f32_e32 v46, v47, v46
	v_div_scale_f32 v47, vcc, 1.0, v41, 1.0
	v_mul_f32_e32 v49, v47, v46
	v_fma_f32 v52, -v45, v49, v47
	v_fmac_f32_e32 v49, v52, v46
	v_fma_f32 v45, -v45, v49, v47
	v_div_fmas_f32 v45, v45, v46, v49
	v_div_fixup_f32 v41, v45, v41, 1.0
	v_lshlrev_b32_e32 v45, 16, v16
	v_mul_f32_e32 v47, 0xbfb8aa3b, v45
	v_exp_f32_e32 v47, v47
	v_and_b32_e32 v46, 0xffff0000, v16
	v_mul_f32_e32 v36, v36, v41
	v_mul_f32_e32 v37, v37, v41
	v_add_f32_e32 v47, 1.0, v47
	v_div_scale_f32 v49, s[0:1], v47, v47, v45
	v_rcp_f32_e32 v52, v49
	v_mul_f32_e32 v43, v43, v41
	v_mul_f32_e32 v44, v44, v41
	v_mul_f32_e32 v38, v38, v41
	v_fma_f32 v53, -v49, v52, 1.0
	v_fmac_f32_e32 v52, v53, v52
	v_div_scale_f32 v53, vcc, v45, v47, v45
	v_mul_f32_e32 v54, v53, v52
	v_fma_f32 v55, -v49, v54, v53
	v_fmac_f32_e32 v54, v55, v52
	v_fma_f32 v49, -v49, v54, v53
	v_div_fmas_f32 v49, v49, v52, v54
	v_div_fixup_f32 v45, v49, v47, v45
	v_mul_f32_e32 v47, 0xbfb8aa3b, v46
	v_exp_f32_e32 v47, v47
	v_mul_f32_e32 v36, v45, v36
	v_and_b32_e32 v45, 0xffff0000, v17
	v_mul_f32_e32 v42, v42, v41
	v_add_f32_e32 v47, 1.0, v47
	v_div_scale_f32 v49, s[0:1], v47, v47, v46
	v_rcp_f32_e32 v52, v49
	v_mul_f32_e32 v39, v39, v41
	v_mul_f32_e32 v40, v40, v41
	v_fma_f32 v53, -v49, v52, 1.0
	v_fmac_f32_e32 v52, v53, v52
	v_div_scale_f32 v53, vcc, v46, v47, v46
	v_mul_f32_e32 v54, v53, v52
	v_fma_f32 v55, -v49, v54, v53
	v_fmac_f32_e32 v54, v55, v52
	v_fma_f32 v49, -v49, v54, v53
	v_div_fmas_f32 v49, v49, v52, v54
	v_div_fixup_f32 v46, v49, v47, v46
	v_mul_f32_e32 v37, v46, v37
	v_cvt_pk_bf16_f32 v36, v36, v37
	v_lshlrev_b32_e32 v37, 16, v17
	v_mul_f32_e32 v46, 0xbfb8aa3b, v37
	v_exp_f32_e32 v46, v46
	s_nop 0
	v_add_f32_e32 v46, 1.0, v46
	v_div_scale_f32 v47, s[0:1], v46, v46, v37
	v_rcp_f32_e32 v49, v47
	s_nop 0
	v_fma_f32 v52, -v47, v49, 1.0
	v_fmac_f32_e32 v49, v52, v49
	v_div_scale_f32 v52, vcc, v37, v46, v37
	v_mul_f32_e32 v53, v52, v49
	v_fma_f32 v54, -v47, v53, v52
	v_fmac_f32_e32 v53, v54, v49
	v_fma_f32 v47, -v47, v53, v52
	v_div_fmas_f32 v47, v47, v49, v53
	v_div_fixup_f32 v37, v47, v46, v37
	v_mul_f32_e32 v46, 0xbfb8aa3b, v45
	v_exp_f32_e32 v46, v46
	v_mul_f32_e32 v37, v37, v43
	v_add_f32_e32 v46, 1.0, v46
	v_div_scale_f32 v47, s[0:1], v46, v46, v45
	v_rcp_f32_e32 v49, v47
	s_nop 0
	v_fma_f32 v52, -v47, v49, 1.0
	v_fmac_f32_e32 v49, v52, v49
	v_div_scale_f32 v52, vcc, v45, v46, v45
	v_mul_f32_e32 v53, v52, v49
	v_fma_f32 v54, -v47, v53, v52
	v_fmac_f32_e32 v53, v54, v49
	v_fma_f32 v47, -v47, v53, v52
	v_div_fmas_f32 v47, v47, v49, v53
	v_div_fixup_f32 v45, v47, v46, v45
	v_mul_f32_e32 v43, v45, v44
	v_cvt_pk_bf16_f32 v37, v37, v43
	v_lshlrev_b32_e32 v43, 16, v18
	v_mul_f32_e32 v45, 0xbfb8aa3b, v43
	v_exp_f32_e32 v45, v45
	v_and_b32_e32 v44, 0xffff0000, v18
	v_add_f32_e32 v45, 1.0, v45
	v_div_scale_f32 v46, s[0:1], v45, v45, v43
	v_rcp_f32_e32 v47, v46
	s_nop 0
	v_fma_f32 v49, -v46, v47, 1.0
	v_fmac_f32_e32 v47, v49, v47
	v_div_scale_f32 v49, vcc, v43, v45, v43
	v_mul_f32_e32 v52, v49, v47
	v_fma_f32 v53, -v46, v52, v49
	v_fmac_f32_e32 v52, v53, v47
	v_fma_f32 v46, -v46, v52, v49
	v_div_fmas_f32 v46, v46, v47, v52
	v_div_fixup_f32 v43, v46, v45, v43
	v_mul_f32_e32 v45, 0xbfb8aa3b, v44
	v_exp_f32_e32 v45, v45
	v_mul_f32_e32 v38, v43, v38
	v_and_b32_e32 v43, 0xffff0000, v19
	v_add_f32_e32 v45, 1.0, v45
	v_div_scale_f32 v46, s[0:1], v45, v45, v44
	v_rcp_f32_e32 v47, v46
	s_nop 0
	v_fma_f32 v49, -v46, v47, 1.0
	v_fmac_f32_e32 v47, v49, v47
	v_div_scale_f32 v49, vcc, v44, v45, v44
	v_mul_f32_e32 v52, v49, v47
	v_fma_f32 v53, -v46, v52, v49
	v_fmac_f32_e32 v52, v53, v47
	v_fma_f32 v46, -v46, v52, v49
	v_div_fmas_f32 v46, v46, v47, v52
	v_div_fixup_f32 v44, v46, v45, v44
	v_mul_f32_e32 v42, v44, v42
	v_cvt_pk_bf16_f32 v38, v38, v42
	v_lshlrev_b32_e32 v42, 16, v19
	v_mul_f32_e32 v41, 0xbfb8aa3b, v42
	v_exp_f32_e32 v41, v41
	s_nop 0
	v_add_f32_e32 v41, 1.0, v41
	v_div_scale_f32 v44, s[0:1], v41, v41, v42
	v_rcp_f32_e32 v45, v44
	s_nop 0
	v_fma_f32 v46, -v44, v45, 1.0
	v_fmac_f32_e32 v45, v46, v45
	v_div_scale_f32 v46, vcc, v42, v41, v42
	v_mul_f32_e32 v47, v46, v45
	v_fma_f32 v49, -v44, v47, v46
	v_fmac_f32_e32 v47, v49, v45
	v_fma_f32 v44, -v44, v47, v46
	v_div_fmas_f32 v44, v44, v45, v47
	v_div_fixup_f32 v41, v44, v41, v42
	v_mul_f32_e32 v42, 0xbfb8aa3b, v43
	v_exp_f32_e32 v42, v42
	v_mul_f32_e32 v39, v41, v39
	v_add_f32_e32 v42, 1.0, v42
	v_div_scale_f32 v44, s[0:1], v42, v42, v43
	v_rcp_f32_e32 v45, v44
	s_lshl_b64 s[0:1], s[40:41], 10
	v_fma_f32 v46, -v44, v45, 1.0
	v_fmac_f32_e32 v45, v46, v45
	v_div_scale_f32 v46, vcc, v43, v42, v43
	v_mul_f32_e32 v47, v46, v45
	v_fma_f32 v49, -v44, v47, v46
	v_fmac_f32_e32 v47, v49, v45
	v_fma_f32 v44, -v44, v47, v46
	v_div_fmas_f32 v44, v44, v45, v47
	v_div_fixup_f32 v42, v44, v42, v43
	v_mul_f32_e32 v40, v42, v40
	v_cvt_pk_bf16_f32 v39, v39, v40
	v_lshl_add_u64 v[40:41], v[50:51], 0, s[0:1]
	global_store_dwordx4 v[40:41], v[36:39], off
	s_branch .LBB0_1142

; #define GAS __attribute__((address_space(1)))
; __device__ __forceinline__ unsigned cvt_pk_bf16(float lo, float hi) { unsigned r; asm volatile("v_cvt_pk_bf16_f32 %0, %1, %2" : "=v"(r) : "v"(lo), "v"(hi)); return r; }
; __device__ __forceinline__ float bf_lo(unsigned w) { return __uint_as_float(w << 16); }
; __device__ __forceinline__ float bf_hi(unsigned w) { return __uint_as_float(w & 0xffff0000u); }
; __device__ __forceinline__ void norm_phase(const Frame& F, const float* g) {
;     ...
;         for (int k = 0; k < 2; ++k) { const int r = r0 + k * F.NGW; if (r < MT) { GAS u32x4* ap = (GAS u32x4*)(A + (size_t)r * D) + F.lane; float ss = 0.f;
; #pragma unroll
;             for (int j = 0; j < 4; ++j)
; #pragma unroll
;                 for (int e = 0; e < 4; ++e) { const float x = bf_lo(w[k][j][e]), y = bf_hi(w[k][j][e]); ss += x * x + y * y; }
;             const float rstd = 1.0f / sqrtf(wave_sum(ss) * (1.f / D) + NORM_EPS);
; #pragma unroll
;             for (int j = 0; j < 4; ++j) { const f32x4 g0 = *((const GAS f32x4*)g + 2 * (F.lane + 64 * j)), g1 = *((const GAS f32x4*)g + 2 * (F.lane + 64 * j) + 1); u32x4 o;
;                 o.x = cvt_pk_bf16(bf_lo(w[k][j].x) * rstd * g0[0], bf_hi(w[k][j].x) * rstd * g0[1]); o.y = cvt_pk_bf16(bf_lo(w[k][j].y) * rstd * g0[2], bf_hi(w[k][j].y) * rstd * g0[3]);
;                 o.z = cvt_pk_bf16(bf_lo(w[k][j].z) * rstd * g1[0], bf_hi(w[k][j].z) * rstd * g1[1]); o.w = cvt_pk_bf16(bf_lo(w[k][j].w) * rstd * g1[2], bf_hi(w[k][j].w) * rstd * g1[3]);
;                 ap[64 * j] = o; } } }
.LBB0_1289:
	s_waitcnt vmcnt(0)
	v_and_b32_e32 v57, 0xffff0000, v28
	v_and_b32_e32 v58, 0xffff0000, v29
	v_lshlrev_b32_e32 v59, 16, v28
	v_mul_f32_e32 v28, v57, v57
	v_lshlrev_b32_e32 v60, 16, v29
	v_mul_f32_e32 v29, v58, v58
	v_fmac_f32_e32 v28, v59, v59
	v_fmac_f32_e32 v29, v60, v60
	v_and_b32_e32 v61, 0xffff0000, v30
	v_add_f32_e32 v28, v28, v29
	v_lshlrev_b32_e32 v62, 16, v30
	v_mul_f32_e32 v29, v61, v61
	v_fmac_f32_e32 v29, v62, v62
	v_and_b32_e32 v63, 0xffff0000, v31
	v_add_f32_e32 v28, v29, v28
	v_lshlrev_b32_e32 v64, 16, v31
	v_mul_f32_e32 v29, v63, v63
	v_and_b32_e32 v55, 0xffff0000, v24
	v_fmac_f32_e32 v29, v64, v64
	v_lshlrev_b32_e32 v56, 16, v24
	v_mul_f32_e32 v24, v55, v55
	v_and_b32_e32 v53, 0xffff0000, v25
	v_add_f32_e32 v28, v29, v28
	v_fmac_f32_e32 v24, v56, v56
	v_lshlrev_b32_e32 v54, 16, v25
	v_mul_f32_e32 v25, v53, v53
	v_add_f32_e32 v24, v24, v28
	v_fmac_f32_e32 v25, v54, v54
	v_and_b32_e32 v51, 0xffff0000, v26
	v_add_f32_e32 v24, v25, v24
	v_lshlrev_b32_e32 v52, 16, v26
	v_mul_f32_e32 v25, v51, v51
	v_fmac_f32_e32 v25, v52, v52
	v_and_b32_e32 v49, 0xffff0000, v27
	v_add_f32_e32 v24, v25, v24
	v_lshlrev_b32_e32 v50, 16, v27
	v_mul_f32_e32 v25, v49, v49
	v_and_b32_e32 v47, 0xffff0000, v20
	v_fmac_f32_e32 v25, v50, v50
	v_lshlrev_b32_e32 v48, 16, v20
	v_mul_f32_e32 v20, v47, v47
	v_and_b32_e32 v45, 0xffff0000, v21
	v_add_f32_e32 v24, v25, v24
	v_fmac_f32_e32 v20, v48, v48
	v_lshlrev_b32_e32 v46, 16, v21
	v_mul_f32_e32 v21, v45, v45
	v_add_f32_e32 v20, v20, v24
	v_fmac_f32_e32 v21, v46, v46
	v_and_b32_e32 v43, 0xffff0000, v22
	v_add_f32_e32 v20, v21, v20
	v_lshlrev_b32_e32 v44, 16, v22
	v_mul_f32_e32 v21, v43, v43
	v_fmac_f32_e32 v21, v44, v44
	v_and_b32_e32 v31, 0xffff0000, v23
	v_add_f32_e32 v20, v21, v20
	v_lshlrev_b32_e32 v42, 16, v23
	v_mul_f32_e32 v21, v31, v31
	v_and_b32_e32 v22, 0xffff0000, v16
	v_fmac_f32_e32 v21, v42, v42
	v_lshlrev_b32_e32 v23, 16, v16
	v_mul_f32_e32 v16, v22, v22
	v_and_b32_e32 v24, 0xffff0000, v17
	v_add_f32_e32 v20, v21, v20
	v_fmac_f32_e32 v16, v23, v23
	v_lshlrev_b32_e32 v25, 16, v17
	v_mul_f32_e32 v17, v24, v24
	v_add_f32_e32 v16, v16, v20
	v_fmac_f32_e32 v17, v25, v25
	v_and_b32_e32 v26, 0xffff0000, v18
	v_add_f32_e32 v16, v17, v16
	v_lshlrev_b32_e32 v28, 16, v18
	v_mul_f32_e32 v17, v26, v26
	v_fmac_f32_e32 v17, v28, v28
	v_and_b32_e32 v27, 0xffff0000, v19
	v_add_f32_e32 v16, v17, v16
	v_lshlrev_b32_e32 v29, 16, v19
	v_mul_f32_e32 v17, v27, v27
	v_fmac_f32_e32 v17, v29, v29
	v_add_f32_e32 v16, v17, v16
	s_nop 1
	v_mov_b32_dpp v17, v16 quad_perm:[1,0,3,2] row_mask:0xf bank_mask:0xf
	v_lshl_add_u64 v[20:21], v[34:35], 0, s[0:1]
	s_waitcnt lgkmcnt(0)
	v_add_f32_e32 v16, v16, v17
	s_nop 1
	v_mov_b32_dpp v17, v16 quad_perm:[2,3,0,1] row_mask:0xf bank_mask:0xf
	s_waitcnt lgkmcnt(0)
	v_add_f32_e32 v16, v16, v17
	s_nop 1
	v_mov_b32_dpp v17, v16 row_half_mirror row_mask:0xf bank_mask:0xf
	s_waitcnt lgkmcnt(0)
	v_add_f32_e32 v16, v16, v17
	s_nop 1
	v_mov_b32_dpp v17, v16 row_mirror row_mask:0xf bank_mask:0xf
	s_waitcnt lgkmcnt(0)
	v_add_f32_e32 v16, v16, v17
	v_mov_b32_e32 v17, v16
	s_nop 1
	v_permlane16_swap_b32_e32 v16, v17
	s_waitcnt lgkmcnt(0)
	v_add_f32_e32 v16, v16, v17
	v_mov_b32_e32 v17, v16
	s_nop 1
	v_permlane32_swap_b32_e32 v16, v17
	v_add_f32_e32 v16, v16, v17
	v_fmamk_f32 v16, v16, 0x3a000000, v250
	v_cmp_gt_f32_e32 vcc, s12, v16
	v_mul_f32_e32 v17, 0x4f800000, v16
	s_nop 0
	v_cndmask_b32_e32 v16, v16, v17, vcc
	v_sqrt_f32_e32 v17, v16
	s_nop 0
	v_add_u32_e32 v18, -1, v17
	v_fma_f32 v19, -v18, v17, v16
	v_cmp_ge_f32_e64 s[0:1], 0, v19
	v_add_u32_e32 v19, 1, v17
	s_nop 0
	v_cndmask_b32_e64 v18, v17, v18, s[0:1]
	v_fma_f32 v17, -v19, v17, v16
	v_cmp_lt_f32_e64 s[0:1], 0, v17
	s_nop 1
	v_cndmask_b32_e64 v17, v18, v19, s[0:1]
	v_mul_f32_e32 v18, 0x37800000, v17
	v_cndmask_b32_e32 v17, v17, v18, vcc
	v_cmp_class_f32_e32 vcc, v16, v251
	s_nop 1
	v_cndmask_b32_e32 v16, v17, v16, vcc
	v_div_scale_f32 v17, s[0:1], v16, v16, 1.0
	v_rcp_f32_e32 v18, v17
	s_nop 0
	v_fma_f32 v19, -v17, v18, 1.0
	v_fmac_f32_e32 v18, v19, v18
	v_div_scale_f32 v19, vcc, 1.0, v16, 1.0
	v_mul_f32_e32 v30, v19, v18
	v_fma_f32 v65, -v17, v30, v19
	v_fmac_f32_e32 v30, v65, v18
	v_fma_f32 v17, -v17, v30, v19
	v_div_fmas_f32 v17, v17, v18, v30
	v_div_fixup_f32 v30, v17, v16, 1.0
	v_mul_f32_e32 v57, v30, v57
	v_mul_f32_e32 v59, v30, v59
	v_mul_f32_e32 v58, v30, v58
	v_mul_f32_e32 v56, v30, v56
	v_mul_f32_e32 v52, v30, v52
	v_mul_f32_e32 v51, v30, v51
	v_mul_f32_e32 v55, v30, v55
	v_mul_f32_e32 v54, v30, v54
	v_mul_f32_e32 v53, v30, v53
	v_mul_f32_e32 v48, v30, v48
	v_mul_f32_e32 v44, v30, v44
	v_mul_f32_e32 v43, v30, v43
	v_mul_f32_e32 v47, v30, v47
	v_mul_f32_e32 v46, v30, v46
	v_mul_f32_e32 v45, v30, v45
	v_mul_f32_e32 v23, v30, v23
	v_mul_f32_e32 v22, v30, v22
	v_mul_f32_e32 v24, v30, v24
	s_andn2_b64 vcc, exec, s[30:31]
	v_mul_f32_e32 v57, v133, v57
	v_mul_f32_e32 v59, v132, v59
	v_cvt_pk_bf16_f32 v66, v59, v57
	v_mul_f32_e32 v57, v30, v60
	v_mul_f32_e32 v57, v134, v57
	v_mul_f32_e32 v58, v135, v58
	v_cvt_pk_bf16_f32 v67, v57, v58
	v_mul_f32_e32 v57, v30, v62
	v_mul_f32_e32 v16, v128, v57
	v_mul_f32_e32 v57, v30, v61
	v_mul_f32_e32 v17, v129, v57
	v_cvt_pk_bf16_f32 v68, v16, v17
	v_mul_f32_e32 v16, v30, v64
	v_mul_f32_e32 v17, v30, v63
	v_mul_f32_e32 v16, v130, v16
	v_mul_f32_e32 v17, v131, v17
	v_cvt_pk_bf16_f32 v69, v16, v17
	global_store_dwordx4 v[20:21], v[66:69], off
	v_mul_f32_e32 v16, v52, v136
	v_mul_f32_e32 v56, v56, v140
	v_mul_f32_e32 v17, v51, v137
	v_mul_f32_e32 v55, v55, v141
	v_cvt_pk_bf16_f32 v56, v56, v55
	v_mul_f32_e32 v54, v54, v142
	v_mul_f32_e32 v53, v53, v143
	v_cvt_pk_bf16_f32 v57, v54, v53
	v_cvt_pk_bf16_f32 v58, v16, v17
	v_mul_f32_e32 v16, v30, v50
	v_mul_f32_e32 v17, v30, v49
	v_mul_f32_e32 v16, v16, v138
	v_mul_f32_e32 v17, v17, v139
	v_cvt_pk_bf16_f32 v59, v16, v17
	global_store_dwordx4 v[20:21], v[56:59], off offset:1024
	v_mul_f32_e32 v16, v44, v144
	v_mul_f32_e32 v48, v48, v148
	v_mul_f32_e32 v17, v43, v145
	v_mul_f32_e32 v47, v47, v149
	v_cvt_pk_bf16_f32 v48, v48, v47
	v_mul_f32_e32 v46, v46, v150
	v_mul_f32_e32 v45, v45, v151
	v_cvt_pk_bf16_f32 v49, v46, v45
	v_cvt_pk_bf16_f32 v50, v16, v17
	v_mul_f32_e32 v16, v30, v42
	v_mul_f32_e32 v17, v30, v31
	v_mul_f32_e32 v16, v16, v146
	v_mul_f32_e32 v17, v17, v147
	v_cvt_pk_bf16_f32 v51, v16, v17
	global_store_dwordx4 v[20:21], v[48:51], off offset:2048
	v_mul_f32_e32 v23, v23, v156
	v_mul_f32_e32 v22, v22, v157
	v_cvt_pk_bf16_f32 v22, v23, v22
	v_mul_f32_e32 v23, v30, v25
	v_mul_f32_e32 v23, v23, v158
	v_mul_f32_e32 v24, v24, v159
	v_cvt_pk_bf16_f32 v23, v23, v24
	v_mul_f32_e32 v24, v30, v28
	v_mul_f32_e32 v16, v24, v152
	v_mul_f32_e32 v24, v30, v26
	v_mul_f32_e32 v17, v24, v153
	v_cvt_pk_bf16_f32 v24, v16, v17
	v_mul_f32_e32 v16, v30, v29
	v_mul_f32_e32 v17, v30, v27
	v_mul_f32_e32 v16, v16, v154
	v_mul_f32_e32 v17, v17, v155
	v_cvt_pk_bf16_f32 v25, v16, v17
	global_store_dwordx4 v[20:21], v[22:25], off offset:3072
	s_cbranch_vccnz .LBB0_1286
; #define GAS __attribute__((address_space(1)))
; __device__ __forceinline__ unsigned cvt_pk_bf16(float lo, float hi) { unsigned r; asm volatile("v_cvt_pk_bf16_f32 %0, %1, %2" : "=v"(r) : "v"(lo), "v"(hi)); return r; }
; __device__ __forceinline__ float bf_lo(unsigned w) { return __uint_as_float(w << 16); }
; __device__ __forceinline__ float bf_hi(unsigned w) { return __uint_as_float(w & 0xffff0000u); }
; __device__ __forceinline__ void norm_phase(const Frame& F, const float* g) {
;     ...
;         for (int k = 0; k < 2; ++k) { const int r = r0 + k * F.NGW; if (r < MT) { GAS u32x4* ap = (GAS u32x4*)(A + (size_t)r * D) + F.lane; float ss = 0.f;
; #pragma unroll
;             for (int j = 0; j < 4; ++j)
; #pragma unroll
;                 for (int e = 0; e < 4; ++e) { const float x = bf_lo(w[k][j][e]), y = bf_hi(w[k][j][e]); ss += x * x + y * y; }
;             const float rstd = 1.0f / sqrtf(wave_sum(ss) * (1.f / D) + NORM_EPS);
; #pragma unroll
;             for (int j = 0; j < 4; ++j) { const f32x4 g0 = *((const GAS f32x4*)g + 2 * (F.lane + 64 * j)), g1 = *((const GAS f32x4*)g + 2 * (F.lane + 64 * j) + 1); u32x4 o;
;                 o.x = cvt_pk_bf16(bf_lo(w[k][j].x) * rstd * g0[0], bf_hi(w[k][j].x) * rstd * g0[1]); o.y = cvt_pk_bf16(bf_lo(w[k][j].y) * rstd * g0[2], bf_hi(w[k][j].y) * rstd * g0[3]);
;                 o.z = cvt_pk_bf16(bf_lo(w[k][j].z) * rstd * g1[0], bf_hi(w[k][j].z) * rstd * g1[1]); o.w = cvt_pk_bf16(bf_lo(w[k][j].w) * rstd * g1[2], bf_hi(w[k][j].w) * rstd * g1[3]);
;                 ap[64 * j] = o; } } }
	v_and_b32_e32 v57, 0xffff0000, v12
	v_and_b32_e32 v58, 0xffff0000, v13
	v_lshlrev_b32_e32 v59, 16, v12
	v_mul_f32_e32 v16, v57, v57
	v_lshlrev_b32_e32 v60, 16, v13
	v_mul_f32_e32 v17, v58, v58
	v_fmac_f32_e32 v16, v59, v59
	v_fmac_f32_e32 v17, v60, v60
	v_and_b32_e32 v61, 0xffff0000, v14
	v_add_f32_e32 v16, v16, v17
	v_lshlrev_b32_e32 v62, 16, v14
	v_mul_f32_e32 v17, v61, v61
	v_fmac_f32_e32 v17, v62, v62
	v_and_b32_e32 v63, 0xffff0000, v15
	v_add_f32_e32 v16, v17, v16
	v_lshlrev_b32_e32 v64, 16, v15
	v_mul_f32_e32 v17, v63, v63
	v_fmac_f32_e32 v17, v64, v64
	v_and_b32_e32 v55, 0xffff0000, v8
	v_add_f32_e32 v16, v17, v16
	v_lshlrev_b32_e32 v56, 16, v8
	v_mul_f32_e32 v17, v55, v55
	v_fmac_f32_e32 v17, v56, v56
	v_and_b32_e32 v53, 0xffff0000, v9
	v_add_f32_e32 v16, v17, v16
	v_lshlrev_b32_e32 v54, 16, v9
	v_mul_f32_e32 v17, v53, v53
	v_fmac_f32_e32 v17, v54, v54
	v_and_b32_e32 v51, 0xffff0000, v10
	v_add_f32_e32 v16, v17, v16
	v_lshlrev_b32_e32 v52, 16, v10
	v_mul_f32_e32 v17, v51, v51
	v_fmac_f32_e32 v17, v52, v52
	v_and_b32_e32 v49, 0xffff0000, v11
	v_add_f32_e32 v16, v17, v16
	v_lshlrev_b32_e32 v50, 16, v11
	v_mul_f32_e32 v17, v49, v49
	v_fmac_f32_e32 v17, v50, v50
	v_and_b32_e32 v47, 0xffff0000, v4
	v_add_f32_e32 v16, v17, v16
	v_lshlrev_b32_e32 v48, 16, v4
	v_mul_f32_e32 v17, v47, v47
	v_fmac_f32_e32 v17, v48, v48
	v_and_b32_e32 v45, 0xffff0000, v5
	v_add_f32_e32 v16, v17, v16
	v_lshlrev_b32_e32 v46, 16, v5
	v_mul_f32_e32 v17, v45, v45
	v_fmac_f32_e32 v17, v46, v46
	v_and_b32_e32 v43, 0xffff0000, v6
	v_add_f32_e32 v16, v17, v16
	v_lshlrev_b32_e32 v44, 16, v6
	v_mul_f32_e32 v17, v43, v43
	v_fmac_f32_e32 v17, v44, v44
	v_and_b32_e32 v31, 0xffff0000, v7
	v_add_f32_e32 v16, v17, v16
	v_lshlrev_b32_e32 v42, 16, v7
	v_mul_f32_e32 v17, v31, v31
	v_fmac_f32_e32 v17, v42, v42
	v_and_b32_e32 v28, 0xffff0000, v0
	v_add_f32_e32 v16, v17, v16
	v_lshlrev_b32_e32 v29, 16, v0
	v_mul_f32_e32 v17, v28, v28
	v_fmac_f32_e32 v17, v29, v29
	v_and_b32_e32 v26, 0xffff0000, v1
	v_add_f32_e32 v16, v17, v16
	v_lshlrev_b32_e32 v27, 16, v1
	v_mul_f32_e32 v17, v26, v26
	v_fmac_f32_e32 v17, v27, v27
	v_and_b32_e32 v24, 0xffff0000, v2
	v_add_f32_e32 v16, v17, v16
	v_lshlrev_b32_e32 v25, 16, v2
	v_mul_f32_e32 v17, v24, v24
	v_fmac_f32_e32 v17, v25, v25
	v_and_b32_e32 v22, 0xffff0000, v3
	v_add_f32_e32 v16, v17, v16
	v_lshlrev_b32_e32 v23, 16, v3
	v_mul_f32_e32 v17, v22, v22
	v_fmac_f32_e32 v17, v23, v23
	v_add_f32_e32 v16, v17, v16
	s_nop 1
	v_mov_b32_dpp v17, v16 quad_perm:[1,0,3,2] row_mask:0xf bank_mask:0xf
	s_ashr_i32 s29, s28, 31
	s_lshl_b64 s[0:1], s[28:29], 12
	v_lshl_add_u64 v[20:21], v[34:35], 0, s[0:1]
	s_waitcnt lgkmcnt(0)
	v_add_f32_e32 v16, v16, v17
	s_nop 1
	v_mov_b32_dpp v17, v16 quad_perm:[2,3,0,1] row_mask:0xf bank_mask:0xf
	s_waitcnt lgkmcnt(0)
	v_add_f32_e32 v16, v16, v17
	s_nop 1
	v_mov_b32_dpp v17, v16 row_half_mirror row_mask:0xf bank_mask:0xf
	s_waitcnt lgkmcnt(0)
	v_add_f32_e32 v16, v16, v17
	s_nop 1
	v_mov_b32_dpp v17, v16 row_mirror row_mask:0xf bank_mask:0xf
	s_waitcnt lgkmcnt(0)
	v_add_f32_e32 v16, v16, v17
	v_mov_b32_e32 v17, v16
	s_nop 1
	v_permlane16_swap_b32_e32 v16, v17
	s_waitcnt lgkmcnt(0)
	v_add_f32_e32 v16, v16, v17
	v_mov_b32_e32 v17, v16
	s_nop 1
	v_permlane32_swap_b32_e32 v16, v17
	v_add_f32_e32 v16, v16, v17
	v_fmamk_f32 v16, v16, 0x3a000000, v250
	v_cmp_gt_f32_e32 vcc, s12, v16
	v_mul_f32_e32 v17, 0x4f800000, v16
	s_nop 0
	v_cndmask_b32_e32 v16, v16, v17, vcc
	v_sqrt_f32_e32 v17, v16
	s_nop 0
	v_add_u32_e32 v18, -1, v17
	v_fma_f32 v19, -v18, v17, v16
	v_cmp_ge_f32_e64 s[0:1], 0, v19
	v_add_u32_e32 v19, 1, v17
	s_nop 0
	v_cndmask_b32_e64 v18, v17, v18, s[0:1]
	v_fma_f32 v17, -v19, v17, v16
	v_cmp_lt_f32_e64 s[0:1], 0, v17
	s_nop 1
	v_cndmask_b32_e64 v17, v18, v19, s[0:1]
	v_mul_f32_e32 v18, 0x37800000, v17
	v_cndmask_b32_e32 v17, v17, v18, vcc
	v_cmp_class_f32_e32 vcc, v16, v251
	s_nop 1
	v_cndmask_b32_e32 v16, v17, v16, vcc
	v_div_scale_f32 v17, s[0:1], v16, v16, 1.0
	v_rcp_f32_e32 v18, v17
	s_nop 0
	v_fma_f32 v19, -v17, v18, 1.0
	v_fmac_f32_e32 v18, v19, v18
	v_div_scale_f32 v19, vcc, 1.0, v16, 1.0
	v_mul_f32_e32 v30, v19, v18
	v_fma_f32 v65, -v17, v30, v19
	v_fmac_f32_e32 v30, v65, v18
	v_fma_f32 v17, -v17, v30, v19
	v_div_fmas_f32 v17, v17, v18, v30
	v_div_fixup_f32 v30, v17, v16, 1.0
	v_mul_f32_e32 v57, v30, v57
	v_mul_f32_e32 v59, v30, v59
	v_mul_f32_e32 v58, v30, v58
	v_mul_f32_e32 v56, v30, v56
	v_mul_f32_e32 v52, v30, v52
	v_mul_f32_e32 v51, v30, v51
	v_mul_f32_e32 v55, v30, v55
	v_mul_f32_e32 v54, v30, v54
	v_mul_f32_e32 v53, v30, v53
	v_mul_f32_e32 v48, v30, v48
	v_mul_f32_e32 v44, v30, v44
	v_mul_f32_e32 v43, v30, v43
	v_mul_f32_e32 v47, v30, v47
	v_mul_f32_e32 v46, v30, v46
	v_mul_f32_e32 v45, v30, v45
	v_mul_f32_e32 v25, v30, v25
	v_mul_f32_e32 v24, v30, v24
	v_mul_f32_e32 v29, v30, v29
	v_mul_f32_e32 v28, v30, v28
	v_mul_f32_e32 v27, v30, v27
	v_mul_f32_e32 v26, v30, v26
	v_mul_f32_e32 v57, v133, v57
	v_mul_f32_e32 v59, v132, v59
	v_cvt_pk_bf16_f32 v66, v59, v57
	v_mul_f32_e32 v57, v30, v60
	v_mul_f32_e32 v57, v134, v57
	v_mul_f32_e32 v58, v135, v58
	v_cvt_pk_bf16_f32 v67, v57, v58
	v_mul_f32_e32 v57, v30, v62
	v_mul_f32_e32 v16, v128, v57
	v_mul_f32_e32 v57, v30, v61
	v_mul_f32_e32 v17, v129, v57
	v_cvt_pk_bf16_f32 v68, v16, v17
	v_mul_f32_e32 v16, v30, v64
	v_mul_f32_e32 v17, v30, v63
	v_mul_f32_e32 v16, v130, v16
	v_mul_f32_e32 v17, v131, v17
	v_cvt_pk_bf16_f32 v69, v16, v17
	global_store_dwordx4 v[20:21], v[66:69], off
	v_mul_f32_e32 v16, v52, v136
	v_mul_f32_e32 v56, v56, v140
	v_mul_f32_e32 v17, v51, v137
	v_mul_f32_e32 v55, v55, v141
	v_cvt_pk_bf16_f32 v56, v56, v55
	v_mul_f32_e32 v54, v54, v142
	v_mul_f32_e32 v53, v53, v143
	v_cvt_pk_bf16_f32 v57, v54, v53
	v_cvt_pk_bf16_f32 v58, v16, v17
	v_mul_f32_e32 v16, v30, v50
	v_mul_f32_e32 v17, v30, v49
	v_mul_f32_e32 v16, v16, v138
	v_mul_f32_e32 v17, v17, v139
	v_cvt_pk_bf16_f32 v59, v16, v17
	global_store_dwordx4 v[20:21], v[56:59], off offset:1024
	v_mul_f32_e32 v16, v44, v144
	v_mul_f32_e32 v48, v48, v148
	v_mul_f32_e32 v17, v43, v145
	v_mul_f32_e32 v47, v47, v149
	v_cvt_pk_bf16_f32 v48, v48, v47
	v_mul_f32_e32 v46, v46, v150
	v_mul_f32_e32 v45, v45, v151
	v_cvt_pk_bf16_f32 v49, v46, v45
	v_cvt_pk_bf16_f32 v50, v16, v17
	v_mul_f32_e32 v16, v30, v42
	v_mul_f32_e32 v17, v30, v31
	v_mul_f32_e32 v16, v16, v146
	v_mul_f32_e32 v17, v17, v147
	v_cvt_pk_bf16_f32 v51, v16, v17
	global_store_dwordx4 v[20:21], v[48:51], off offset:2048
	v_mul_f32_e32 v16, v25, v152
	v_mul_f32_e32 v17, v24, v153
	v_mul_f32_e32 v29, v29, v156
	v_mul_f32_e32 v28, v28, v157
	v_cvt_pk_bf16_f32 v42, v29, v28
	v_mul_f32_e32 v27, v27, v158
	v_mul_f32_e32 v26, v26, v159
	v_cvt_pk_bf16_f32 v43, v27, v26
	v_cvt_pk_bf16_f32 v44, v16, v17
	v_mul_f32_e32 v16, v30, v23
	v_mul_f32_e32 v17, v30, v22
	v_mul_f32_e32 v16, v16, v154
	v_mul_f32_e32 v17, v17, v155
	v_cvt_pk_bf16_f32 v45, v16, v17
	global_store_dwordx4 v[20:21], v[42:45], off offset:3072
	s_branch .LBB0_1286

; #define GAS __attribute__((address_space(1)))
; __device__ __forceinline__ float bf_lo(unsigned w) { return __uint_as_float(w << 16); }
; __device__ __forceinline__ float bf_hi(unsigned w) { return __uint_as_float(w & 0xffff0000u); }
; __device__ __forceinline__ void final_phase(const Frame& F) {
;     ...
;     for (int i = F.gw; i < NREAL; i += F.NGW) {
;         int r; if (i < NP * SP) r = (i / SP) * LP_P + PADF + NMETA + (i % SP); else { const int k = i - NP * SP; r = ROWS0 + (k / SS) * LP_S + PADF + NMETA + (k % SS); }
;         const GAS u32x4* hp = (const GAS u32x4*)(H + (size_t)r * D) + F.lane; GAS f32x4* op = (GAS f32x4*)(outp + (size_t)i * D);
;         u32x4 w[4]; float ss = 0.f;
; #pragma unroll
;         for (int j = 0; j < 4; ++j) { w[j] = __builtin_nontemporal_load(hp + 64 * j);
; #pragma unroll
;             for (int e = 0; e < 4; ++e) { const float x = bf_lo(w[j][e]), y = bf_hi(w[j][e]); ss += x * x + y * y; } }
;         const float rstd = 1.0f / sqrtf(wave_sum(ss) * (1.f / D) + NORM_EPS);
.LBB0_1861:
	s_ashr_i32 s1, s0, 31
	s_lshl_b64 s[0:1], s[0:1], 12
	v_lshl_add_u64 v[26:27], v[0:1], 0, s[0:1]
	global_load_dwordx4 v[14:17], v[26:27], off nt
	global_load_dwordx4 v[18:21], v[26:27], off offset:1024 nt
	global_load_dwordx4 v[22:25], v[26:27], off offset:2048 nt
	s_nop 0
	global_load_dwordx4 v[26:29], v[26:27], off offset:3072 nt
	s_nop 0
	s_ashr_i32 s19, s18, 31
	s_lshl_b64 s[8:9], s[18:19], 13
	s_add_u32 s20, s4, s8
	s_addc_u32 s21, s5, s9
	s_add_i32 s18, s18, s14
	s_cmp_lt_i32 s18, 0x10000
	s_waitcnt vmcnt(0)
	v_lshlrev_b32_e32 v38, 16, v14
	v_and_b32_e32 v39, 0xffff0000, v14
	v_lshlrev_b32_e32 v14, 16, v15
	v_and_b32_e32 v15, 0xffff0000, v15
	v_lshlrev_b32_e32 v40, 16, v16
	v_and_b32_e32 v41, 0xffff0000, v16
	v_lshlrev_b32_e32 v42, 16, v18
	v_and_b32_e32 v43, 0xffff0000, v18
	v_lshlrev_b32_e32 v44, 16, v19
	v_and_b32_e32 v45, 0xffff0000, v19
	v_lshlrev_b32_e32 v46, 16, v20
	v_and_b32_e32 v47, 0xffff0000, v20
	v_lshlrev_b32_e32 v48, 16, v21
	v_and_b32_e32 v49, 0xffff0000, v21
	v_pk_mul_f32 v[18:19], v[38:39], v[38:39]
	v_pk_mul_f32 v[20:21], v[14:15], v[14:15]
	v_lshlrev_b32_e32 v16, 16, v17
	v_and_b32_e32 v17, 0xffff0000, v17
	v_pk_mul_f32 v[58:59], v[40:41], v[40:41]
	v_add_f32_e32 v13, v20, v21
	v_add_f32_e32 v18, v18, v19
	v_pk_mul_f32 v[60:61], v[16:17], v[16:17]
	v_add_f32_e32 v19, v58, v59
	v_add_f32_e32 v13, v18, v13
	v_pk_mul_f32 v[62:63], v[42:43], v[42:43]
	v_add_f32_e32 v20, v60, v61
	v_add_f32_e32 v13, v19, v13
	v_pk_mul_f32 v[64:65], v[44:45], v[44:45]
	v_add_f32_e32 v21, v62, v63
	v_add_f32_e32 v13, v20, v13
	v_pk_mul_f32 v[66:67], v[46:47], v[46:47]
	v_add_f32_e32 v58, v64, v65
	v_add_f32_e32 v13, v21, v13
	v_lshlrev_b32_e32 v50, 16, v22
	v_and_b32_e32 v51, 0xffff0000, v22
	v_pk_mul_f32 v[68:69], v[48:49], v[48:49]
	v_add_f32_e32 v59, v66, v67
	v_add_f32_e32 v13, v58, v13
	v_lshlrev_b32_e32 v22, 16, v23
	v_and_b32_e32 v23, 0xffff0000, v23
	v_pk_mul_f32 v[70:71], v[50:51], v[50:51]
	v_add_f32_e32 v60, v68, v69
	v_add_f32_e32 v13, v59, v13
	v_lshlrev_b32_e32 v52, 16, v24
	v_and_b32_e32 v53, 0xffff0000, v24
	v_pk_mul_f32 v[72:73], v[22:23], v[22:23]
	v_add_f32_e32 v61, v70, v71
	v_add_f32_e32 v13, v60, v13
	v_lshlrev_b32_e32 v24, 16, v25
	v_and_b32_e32 v25, 0xffff0000, v25
	v_pk_mul_f32 v[74:75], v[52:53], v[52:53]
	v_add_f32_e32 v62, v72, v73
	v_add_f32_e32 v13, v61, v13
	v_lshlrev_b32_e32 v54, 16, v26
	v_and_b32_e32 v55, 0xffff0000, v26
	v_pk_mul_f32 v[76:77], v[24:25], v[24:25]
	v_add_f32_e32 v63, v74, v75
	v_add_f32_e32 v13, v62, v13
	v_lshlrev_b32_e32 v26, 16, v27
	v_and_b32_e32 v27, 0xffff0000, v27
	v_pk_mul_f32 v[78:79], v[54:55], v[54:55]
	v_add_f32_e32 v64, v76, v77
	v_add_f32_e32 v13, v63, v13
	v_lshlrev_b32_e32 v56, 16, v28
	v_and_b32_e32 v57, 0xffff0000, v28
	v_pk_mul_f32 v[80:81], v[26:27], v[26:27]
	v_add_f32_e32 v65, v78, v79
	v_add_f32_e32 v13, v64, v13
	v_lshlrev_b32_e32 v28, 16, v29
	v_and_b32_e32 v29, 0xffff0000, v29
	v_pk_mul_f32 v[82:83], v[56:57], v[56:57]
	v_add_f32_e32 v66, v80, v81
	v_add_f32_e32 v13, v65, v13
	v_pk_mul_f32 v[84:85], v[28:29], v[28:29]
	v_add_f32_e32 v67, v82, v83
	v_add_f32_e32 v13, v66, v13
	v_add_f32_e32 v68, v84, v85
	v_add_f32_e32 v13, v67, v13
	v_add_f32_e32 v13, v68, v13
	s_nop 1
	v_mov_b32_dpp v18, v13 quad_perm:[1,0,3,2] row_mask:0xf bank_mask:0xf
	s_waitcnt lgkmcnt(0)
	v_add_f32_e32 v13, v13, v18
	s_nop 1
	v_mov_b32_dpp v18, v13 quad_perm:[2,3,0,1] row_mask:0xf bank_mask:0xf
	s_waitcnt lgkmcnt(0)
	v_add_f32_e32 v13, v13, v18
	s_nop 1
	v_mov_b32_dpp v18, v13 row_half_mirror row_mask:0xf bank_mask:0xf
	s_waitcnt lgkmcnt(0)
; #define GAS __attribute__((address_space(1)))
; __device__ __forceinline__ float bf_lo(unsigned w) { return __uint_as_float(w << 16); }
; __device__ __forceinline__ float bf_hi(unsigned w) { return __uint_as_float(w & 0xffff0000u); }
; __device__ __forceinline__ void final_phase(const Frame& F) {
;     ...
;         const float rstd = 1.0f / sqrtf(wave_sum(ss) * (1.f / D) + NORM_EPS);
; #pragma unroll
;         for (int j = 0; j < 4; ++j) { const int c2 = 2 * (F.lane + 64 * j); const f32x4 g0 = *((const GAS f32x4*)g + c2), g1 = *((const GAS f32x4*)g + c2 + 1);
;             __builtin_nontemporal_store((f32x4){bf_lo(w[j].x) * rstd * g0[0], bf_hi(w[j].x) * rstd * g0[1], bf_lo(w[j].y) * rstd * g0[2], bf_hi(w[j].y) * rstd * g0[3]}, op + c2);
;             __builtin_nontemporal_store((f32x4){bf_lo(w[j].z) * rstd * g1[0], bf_hi(w[j].z) * rstd * g1[1], bf_lo(w[j].w) * rstd * g1[2], bf_hi(w[j].w) * rstd * g1[3]}, op + c2 + 1); }
	v_add_f32_e32 v13, v13, v18
	s_nop 1
	v_mov_b32_dpp v18, v13 row_mirror row_mask:0xf bank_mask:0xf
	s_waitcnt lgkmcnt(0)
	v_add_f32_e32 v13, v13, v18
	v_mov_b32_e32 v18, v13
	s_nop 1
	v_permlane16_swap_b32_e32 v13, v18
	s_waitcnt lgkmcnt(0)
	v_add_f32_e32 v13, v13, v18
	v_mov_b32_e32 v18, v13
	s_nop 1
	v_permlane32_swap_b32_e32 v13, v18
	v_add_f32_e32 v13, v13, v18
	v_fmamk_f32 v13, v13, 0x3a000000, v11
	v_mul_f32_e32 v18, 0x4f800000, v13
	v_cmp_gt_f32_e32 vcc, s6, v13
	s_nop 1
	v_cndmask_b32_e32 v13, v13, v18, vcc
	v_sqrt_f32_e32 v18, v13
	s_nop 0
	v_add_u32_e32 v19, -1, v18
	v_add_u32_e32 v20, 1, v18
	v_fma_f32 v21, -v19, v18, v13
	v_fma_f32 v58, -v20, v18, v13
	v_cmp_ge_f32_e64 s[0:1], 0, v21
	s_nop 1
	v_cndmask_b32_e64 v18, v18, v19, s[0:1]
	v_cmp_lt_f32_e64 s[0:1], 0, v58
	s_nop 1
	v_cndmask_b32_e64 v18, v18, v20, s[0:1]
	v_mul_f32_e32 v19, 0x37800000, v18
	v_cndmask_b32_e32 v18, v18, v19, vcc
	v_cmp_class_f32_e32 vcc, v13, v12
	s_nop 1
	v_cndmask_b32_e32 v13, v18, v13, vcc
	v_div_scale_f32 v18, s[0:1], v13, v13, 1.0
	v_rcp_f32_e32 v19, v18
	v_div_scale_f32 v20, vcc, 1.0, v13, 1.0
	v_fma_f32 v21, -v18, v19, 1.0
	v_fmac_f32_e32 v19, v21, v19
	v_mul_f32_e32 v21, v20, v19
	v_fma_f32 v58, -v18, v21, v20
	v_fmac_f32_e32 v21, v58, v19
	v_fma_f32 v18, -v18, v21, v20
	v_div_fmas_f32 v18, v18, v19, v21
	v_div_fixup_f32 v58, v18, v13, 1.0
	v_pk_mul_f32 v[18:19], v[58:59], v[38:39] op_sel_hi:[0,1]
	v_pk_mul_f32 v[14:15], v[58:59], v[14:15] op_sel_hi:[0,1]
	v_pk_mul_f32 v[38:39], v[58:59], v[40:41] op_sel_hi:[0,1]
	v_pk_mul_f32 v[20:21], v[58:59], v[16:17] op_sel_hi:[0,1]
	v_pk_mul_f32 v[16:17], v[134:135], v[14:15]
	v_pk_mul_f32 v[14:15], v[132:133], v[18:19]
	v_pk_mul_f32 v[20:21], v[130:131], v[20:21]
	v_pk_mul_f32 v[18:19], v[128:129], v[38:39]
	global_store_dwordx4 v8, v[14:17], s[20:21] nt
	global_store_dwordx4 v8, v[18:21], s[20:21] offset:16 nt
	s_nop 0
	v_pk_mul_f32 v[30:31], v[58:59], v[44:45] op_sel_hi:[0,1]
	v_pk_mul_f32 v[32:33], v[58:59], v[42:43] op_sel_hi:[0,1]
	v_pk_mul_f32 v[34:35], v[58:59], v[48:49] op_sel_hi:[0,1]
	v_pk_mul_f32 v[36:37], v[58:59], v[46:47] op_sel_hi:[0,1]
	v_pk_mul_f32 v[22:23], v[58:59], v[22:23] op_sel_hi:[0,1]
	v_pk_mul_f32 v[24:25], v[58:59], v[24:25] op_sel_hi:[0,1]
	v_pk_mul_f32 v[14:15], v[136:137], v[32:33]
	v_pk_mul_f32 v[16:17], v[138:139], v[30:31]
	v_pk_mul_f32 v[18:19], v[140:141], v[36:37]
	v_pk_mul_f32 v[20:21], v[142:143], v[34:35]
	global_store_dwordx4 v8, v[14:17], s[20:21] offset:2048 nt
	global_store_dwordx4 v8, v[18:21], s[20:21] offset:2064 nt
	s_nop 0
	v_pk_mul_f32 v[30:31], v[58:59], v[50:51] op_sel_hi:[0,1]
	v_pk_mul_f32 v[32:33], v[58:59], v[52:53] op_sel_hi:[0,1]
	v_pk_mul_f32 v[14:15], v[30:31], v[144:145]
	v_pk_mul_f32 v[16:17], v[22:23], v[146:147]
	v_pk_mul_f32 v[18:19], v[32:33], v[148:149]
	v_pk_mul_f32 v[20:21], v[24:25], v[150:151]
	global_store_dwordx4 v9, v[14:17], s[20:21] nt
	global_store_dwordx4 v9, v[18:21], s[20:21] offset:16 nt
	s_nop 0
	v_pk_mul_f32 v[22:23], v[58:59], v[26:27] op_sel_hi:[0,1]
	v_pk_mul_f32 v[24:25], v[58:59], v[54:55] op_sel_hi:[0,1]
	v_pk_mul_f32 v[26:27], v[58:59], v[28:29] op_sel_hi:[0,1]
	v_pk_mul_f32 v[28:29], v[58:59], v[56:57] op_sel_hi:[0,1]
	v_pk_mul_f32 v[14:15], v[24:25], v[152:153]
	v_pk_mul_f32 v[16:17], v[22:23], v[154:155]
	v_pk_mul_f32 v[18:19], v[28:29], v[156:157]
	v_pk_mul_f32 v[20:21], v[26:27], v[158:159]
	global_store_dwordx4 v10, v[14:17], s[20:21] nt
	global_store_dwordx4 v10, v[18:21], s[20:21] offset:16 nt
	s_cbranch_scc0 .LBB0_1866
